# conv phase inner loop rewritten by hand: 10-row deep prefetch ring, accumulate-per-row formulation
# speedup vs baseline: 1.0504x; 1.0504x over previous
; __device__ __forceinline__ unsigned xcc_id() { return (unsigned)__builtin_amdgcn_s_getreg((3 << 11) | 20) & 7u; }
; __global__ void __launch_bounds__(512, 2) mega(Params p, int ph_lo, int ph_hi) {
;   extern __shared__ __attribute__((aligned(16))) char shm[];
;   cg::grid_group grid = cg::this_grid();
;   const int swave = __builtin_amdgcn_readfirstlane(threadIdx.x >> 6);
;   unsigned* bar = (unsigned*)(p.ws + OFF_BAR);
;   unsigned info = 0;
;   if (ph_hi - ph_lo > 1) {
;     if (blockIdx.x == 0) for (int i = threadIdx.x; i < 19; i += 512) __hip_atomic_store(bar + 64 * i, 0u, __ATOMIC_RELAXED, __HIP_MEMORY_SCOPE_AGENT);
;     grid.sync();
;     const unsigned myxcc = xcc_id();
;     if (threadIdx.x == 0) {
;       __hip_atomic_fetch_add(bar + 64 * myxcc, 1u, __ATOMIC_RELAXED, __HIP_MEMORY_SCOPE_AGENT);
;       __hip_atomic_fetch_add(bar + 64 * 17, 1u, __ATOMIC_RELAXED, __HIP_MEMORY_SCOPE_AGENT);
;       while (__hip_atomic_load(bar + 64 * 17, __ATOMIC_RELAXED, __HIP_MEMORY_SCOPE_AGENT) < gridDim.x) __builtin_amdgcn_s_sleep(1);
;     }
;     __syncthreads();
;     unsigned nxcc = 0, nmine = 1;
;     for (int i = 0; i < 8; ++i) { const unsigned c = __hip_atomic_load(bar + 64 * i, __ATOMIC_RELAXED, __HIP_MEMORY_SCOPE_AGENT); nxcc += c ? 1u : 0u; if (i == (int)myxcc) nmine = c; }
;     info = __builtin_amdgcn_readfirstlane(myxcc | (nmine << 8) | (nxcc << 24));
;   }
;   unsigned epoch = 0;
;   for (int ph = ph_lo; ph < ph_hi; ++ph) {
.LBB0_21:
	s_load_dwordx16 s[36:51], s[0:1], 0x0
	s_cmp_le_i32 s29, s28
	s_waitcnt lgkmcnt(0)
	v_writelane_b32 v248, s36, 12
	s_nop 1
	v_writelane_b32 v248, s37, 13
	v_writelane_b32 v248, s38, 14
	v_writelane_b32 v248, s39, 15
	v_writelane_b32 v248, s40, 16
	v_writelane_b32 v248, s41, 17
	v_writelane_b32 v248, s42, 18
	v_writelane_b32 v248, s43, 19
	v_writelane_b32 v248, s44, 20
	v_writelane_b32 v248, s45, 21
	v_writelane_b32 v248, s46, 22
	v_writelane_b32 v248, s47, 23
	v_writelane_b32 v248, s48, 24
	v_writelane_b32 v248, s49, 25
	v_writelane_b32 v248, s50, 26
	v_writelane_b32 v248, s51, 27
	s_load_dwordx16 s[36:51], s[0:1], 0x40
	s_waitcnt lgkmcnt(0)
	v_writelane_b32 v248, s36, 28
	s_nop 1
	v_writelane_b32 v248, s37, 29
	v_writelane_b32 v248, s38, 30
	v_writelane_b32 v248, s39, 31
	v_writelane_b32 v248, s40, 32
	v_writelane_b32 v248, s41, 33
	v_writelane_b32 v248, s42, 34
	v_writelane_b32 v248, s43, 35
	v_writelane_b32 v248, s44, 36
	v_writelane_b32 v248, s45, 37
	v_writelane_b32 v248, s46, 38
	v_writelane_b32 v248, s47, 39
	v_writelane_b32 v248, s48, 40
	v_writelane_b32 v248, s49, 41
	v_writelane_b32 v248, s50, 42
	v_writelane_b32 v248, s51, 43
	s_load_dwordx16 s[36:51], s[0:1], 0x80
	s_waitcnt lgkmcnt(0)
	v_writelane_b32 v248, s36, 44
	s_nop 1
	v_writelane_b32 v248, s37, 45
	v_writelane_b32 v248, s38, 46
	v_writelane_b32 v248, s39, 47
	v_writelane_b32 v248, s40, 48
	v_writelane_b32 v248, s41, 49
	v_writelane_b32 v248, s42, 50
	v_writelane_b32 v248, s43, 51
	v_writelane_b32 v248, s44, 52
	v_writelane_b32 v248, s45, 53
	v_writelane_b32 v248, s46, 54
	v_writelane_b32 v248, s47, 55
	v_writelane_b32 v248, s48, 56
	v_writelane_b32 v248, s49, 57
	v_writelane_b32 v248, s50, 58
	v_writelane_b32 v248, s51, 59
	s_cbranch_scc1 .Lexit_near
; __device__ __forceinline__ unsigned xcc_id() { return (unsigned)__builtin_amdgcn_s_getreg((3 << 11) | 20) & 7u; }
; __device__ __forceinline__ int transpose_tiles(int swave, const float* __restrict__ src, int lds_, int Kc, int Nc, bf16_t* __restrict__ dst, int ldd, char* shm, int job0, int bidx, int G) {
;     ...
;   int t0 = (bidx - job0 % G + G) % G;
; __global__ void __launch_bounds__(512, 2) mega(Params p, int ph_lo, int ph_hi) {
;   extern __shared__ __attribute__((aligned(16))) char shm[];
;   cg::grid_group grid = cg::this_grid();
;   const int swave = __builtin_amdgcn_readfirstlane(threadIdx.x >> 6);
;   unsigned* bar = (unsigned*)(p.ws + OFF_BAR);
;   unsigned info = 0;
;   if (ph_hi - ph_lo > 1) {
;     if (blockIdx.x == 0) for (int i = threadIdx.x; i < 19; i += 512) __hip_atomic_store(bar + 64 * i, 0u, __ATOMIC_RELAXED, __HIP_MEMORY_SCOPE_AGENT);
;     grid.sync();
;     const unsigned myxcc = xcc_id();
;     if (threadIdx.x == 0) {
;       __hip_atomic_fetch_add(bar + 64 * myxcc, 1u, __ATOMIC_RELAXED, __HIP_MEMORY_SCOPE_AGENT);
;       __hip_atomic_fetch_add(bar + 64 * 17, 1u, __ATOMIC_RELAXED, __HIP_MEMORY_SCOPE_AGENT);
;       while (__hip_atomic_load(bar + 64 * 17, __ATOMIC_RELAXED, __HIP_MEMORY_SCOPE_AGENT) < gridDim.x) __builtin_amdgcn_s_sleep(1);
;     }
;     __syncthreads();
;     unsigned nxcc = 0, nmine = 1;
;     for (int i = 0; i < 8; ++i) { const unsigned c = __hip_atomic_load(bar + 64 * i, __ATOMIC_RELAXED, __HIP_MEMORY_SCOPE_AGENT); nxcc += c ? 1u : 0u; if (i == (int)myxcc) nmine = c; }
;     info = __builtin_amdgcn_readfirstlane(myxcc | (nmine << 8) | (nxcc << 24));
;   }
;   unsigned epoch = 0;
;   for (int ph = ph_lo; ph < ph_hi; ++ph) {
;     if (ph > ph_lo) { epoch += 1; grid_barrier(bar, epoch, info, swave); }
	s_bfe_u32 s0, s4, 0x100008
	v_writelane_b32 v248, s0, 60
	s_lshr_b32 s0, s4, 24
	s_cmp_lt_u32 s12, 64
	v_writelane_b32 v248, s0, 61
	s_cselect_b64 s[24:25], -1, 0
	s_lshl_b32 s0, s4, 8
	s_and_b32 s0, s0, 0xff00
	s_add_u32 s0, s2, s0
	s_addc_u32 s1, s3, 0
	v_writelane_b32 v248, s0, 62
	s_mov_b32 s90, 0x6dc9c883
	s_mov_b32 s92, 0x54442d18
	v_writelane_b32 v248, s1, 63
	s_movk_i32 s58, 0xff00
	v_readlane_b32 s4, v248, 8
	v_readlane_b32 s6, v248, 10
	v_readlane_b32 s7, v248, 11
	s_add_u32 s86, s6, 0x1ec9d000
	s_addc_u32 s87, s7, 0
	s_add_i32 s2, s67, 0xffffff80
	s_sub_i32 s0, 0x80, s67
	s_max_i32 s3, s2, s0
	v_cvt_f32_u32_e32 v0, s3
	s_lshl_b32 s1, s67, 5
	v_writelane_b32 v247, s1, 0
	s_lshl_b32 s1, s12, 4
	v_rcp_iflag_f32_e32 v0, v0
	s_and_b32 s89, s1, 0x7ffffc00
	v_writelane_b32 v247, s2, 1
	s_lshl_b32 s96, s2, 9
	v_mul_f32_e32 v0, 0x4f7ffffe, v0
	v_cvt_u32_f32_e32 v0, v0
	s_sub_i32 s1, 0, s3
	s_and_b32 s0, s12, 0xffffffc0
	s_lshl_b32 s88, s67, 4
	v_readfirstlane_b32 s2, v0
	s_mul_i32 s1, s1, s2
	s_mul_hi_u32 s1, s2, s1
	s_add_i32 s4, s2, s1
	s_mul_hi_u32 s1, s4, 0x2c0
	s_mul_i32 s1, s1, s3
	s_sub_i32 s1, 0x2c0, s1
	s_lshl_b32 s57, s67, 9
	s_lshl_b32 s84, s67, 3
	s_sub_i32 s2, s1, s3
	s_cmp_ge_u32 s1, s3
	s_cselect_b32 s1, s2, s1
	s_sub_i32 s2, s1, s3
	s_cmp_ge_u32 s1, s3
	s_cselect_b32 s1, s2, s1
	v_writelane_b32 v247, s1, 2
	s_mul_hi_u32 s1, s4, 0x440
	s_mul_i32 s1, s1, s3
	s_sub_i32 s1, 0x440, s1
	s_sub_i32 s2, s1, s3
	s_cmp_ge_u32 s1, s3
	s_cselect_b32 s1, s2, s1
	s_sub_i32 s2, s1, s3
	s_cmp_ge_u32 s1, s3
	s_cselect_b32 s1, s2, s1
	v_writelane_b32 v247, s1, 3
	s_mul_hi_u32 s1, s4, 0x5c0
	s_mul_i32 s1, s1, s3
	s_sub_i32 s1, 0x5c0, s1
	s_sub_i32 s2, s1, s3
	s_cmp_ge_u32 s1, s3
	s_cselect_b32 s1, s2, s1
	s_sub_i32 s2, s1, s3
	s_cmp_ge_u32 s1, s3
	s_cselect_b32 s1, s2, s1
	v_writelane_b32 v247, s1, 4
	s_mul_hi_u32 s1, s4, 0x700
	s_mul_i32 s1, s1, s3
	s_sub_i32 s1, 0x700, s1
	s_sub_i32 s2, s1, s3
	s_cmp_ge_u32 s1, s3
	s_cselect_b32 s1, s2, s1
	s_sub_i32 s2, s1, s3
	s_cmp_ge_u32 s1, s3
	s_cselect_b32 s1, s2, s1
	v_writelane_b32 v247, s1, 5
	s_mul_hi_u32 s1, s4, 0x840
	s_mul_i32 s1, s1, s3
	s_sub_i32 s1, 0x840, s1
	s_sub_i32 s2, s1, s3
	s_cmp_ge_u32 s1, s3
	s_cselect_b32 s1, s2, s1
	s_sub_i32 s2, s1, s3
	v_writelane_b32 v247, s4, 6
	s_cmp_ge_u32 s1, s3
	v_writelane_b32 v247, s3, 7
	s_cselect_b32 s1, s2, s1
	s_abs_i32 s3, s67
	v_cvt_f32_u32_e32 v0, s3
	v_writelane_b32 v247, s1, 8
	s_sub_i32 s1, 0, s3
	v_readlane_b32 s8, v248, 44
	v_rcp_iflag_f32_e32 v0, v0
	v_readlane_b32 s16, v248, 52
	v_readlane_b32 s17, v248, 53
	v_readlane_b32 s14, v248, 50
	v_mul_f32_e32 v0, 0x4f7ffffe, v0
	v_cvt_u32_f32_e32 v0, v0
	v_readlane_b32 s15, v248, 51
	v_readlane_b32 s12, v248, 48
	v_readlane_b32 s22, v248, 58
	v_readfirstlane_b32 s2, v0
	s_mul_i32 s1, s1, s2
	s_mul_hi_u32 s1, s2, s1
	s_add_i32 s4, s2, s1
	s_mul_hi_u32 s1, s4, 0x2c0
	s_mul_i32 s1, s1, s3
	s_sub_i32 s1, 0x2c0, s1
	s_sub_i32 s2, s1, s3
	s_cmp_ge_u32 s1, s3
	s_cselect_b32 s1, s2, s1
	s_sub_i32 s2, s1, s3
	s_cmp_ge_u32 s1, s3
	s_cselect_b32 s1, s2, s1
	v_writelane_b32 v247, s1, 9
	s_mul_hi_u32 s1, s4, 0x3c0
	s_mul_i32 s1, s1, s3
	s_sub_i32 s1, 0x3c0, s1
	s_sub_i32 s2, s1, s3
	s_cmp_ge_u32 s1, s3
	s_cselect_b32 s1, s2, s1
	s_sub_i32 s2, s1, s3
	v_writelane_b32 v247, s4, 10
	s_cmp_ge_u32 s1, s3
	v_writelane_b32 v247, s3, 11
	s_cselect_b32 s1, s2, s1
	v_writelane_b32 v247, s1, 12
	s_lshl_b32 s1, s67, 12
	s_add_i32 s1, s1, 0xfff80000
	v_writelane_b32 v247, s1, 13
	s_add_u32 s1, s16, 0x10000
	v_writelane_b32 v247, s1, 14
	s_addc_u32 s1, s17, 0
	v_writelane_b32 v247, s1, 15
	s_add_u32 s1, s14, 0x10000
	v_writelane_b32 v247, s1, 16
	s_addc_u32 s1, s15, 0
	v_writelane_b32 v247, s1, 17
	s_add_u32 s1, s6, 0x1b9a2600
	v_writelane_b32 v247, s1, 18
	s_addc_u32 s1, s7, 0
	v_writelane_b32 v247, s1, 19
	s_add_u32 s1, s16, 0x10010
	v_writelane_b32 v247, s1, 20
	s_addc_u32 s1, s17, 0
	v_writelane_b32 v247, s1, 21
	s_add_u32 s1, s14, 0x10010
	v_writelane_b32 v247, s1, 22
	s_addc_u32 s1, s15, 0
	v_writelane_b32 v247, s1, 23
	s_add_u32 s1, s6, 0xc000000
	v_writelane_b32 v247, s1, 24
	s_addc_u32 s1, s7, 0
	v_writelane_b32 v247, s1, 25
	v_mbcnt_lo_u32_b32 v0, -1, 0
	v_writelane_b32 v247, s24, 26
	v_mbcnt_hi_u32_b32 v146, -1, v0
	v_add_u32_e32 v147, s0, v146
	v_writelane_b32 v247, s25, 27
	s_add_i32 s0, 0, 0x18000
	v_writelane_b32 v247, s0, 28
	s_add_i32 s0, 0, 0x1c000
	v_writelane_b32 v247, s0, 29
	s_add_i32 s0, 0, 0x10700
	v_writelane_b32 v247, s0, 30
	s_add_i32 s0, 0, 0x11800
	v_writelane_b32 v247, s0, 31
	s_add_i32 s0, 0, 0x14700
	v_writelane_b32 v247, s0, 32
	s_add_i32 s0, 0, 0x14600
	v_writelane_b32 v247, s0, 33
	s_add_i32 s0, 0, 0x12800
	v_writelane_b32 v247, s0, 34
	s_add_i32 s0, 0, 0x14800
	v_writelane_b32 v247, s0, 35
	s_add_i32 s0, 0, 0x17900
	v_writelane_b32 v247, s0, 36
	s_add_i32 s0, 0, 0x1aa00
	v_writelane_b32 v247, s0, 37
	s_add_i32 s0, 0, 0x1db00
	v_writelane_b32 v247, s0, 38
	s_add_i32 s0, 0, 0xdd00
	v_writelane_b32 v247, s0, 39
	s_add_i32 s0, 0, 0xed80
	v_writelane_b32 v247, s0, 40
	s_add_i32 s0, 0, 0xbc00
	v_writelane_b32 v247, s0, 41
	s_add_i32 s0, 0, 0xcc80
	v_writelane_b32 v247, s0, 42
	s_mov_b32 s0, 0
	v_readlane_b32 s23, v248, 59
	v_writelane_b32 v247, s0, 43
	s_movk_i32 s60, 0xff80
	v_cndmask_b32_e64 v133, 0, 1, s[24:25]
	v_mov_b32_e32 v3, 0
	s_movk_i32 s62, 0x1000
	s_mov_b32 s26, 0x800000
	s_movk_i32 s97, 0x7fff
	s_movk_i32 s52, 0x300
	s_movk_i32 s55, 0x1600
	s_mov_b32 s56, 0xbfb8aa3b
	v_mov_b32_e32 v132, 0x358637bd
	s_mov_b32 s64, 0x1ffff
	s_mov_b32 s91, 0x3fc45f30
	s_mov_b32 s93, 0xc01921fb
	v_mov_b32_e32 v148, 0x3ecc95a3
	v_mov_b32_e32 v149, 1
	v_mov_b32_e32 v150, 0xc0b00000
	v_mov_b32_e32 v151, 0xc0a00000
	v_mov_b32_e32 v152, 0x42800000
	v_mov_b32_e32 v134, 0x3f317218
	v_mov_b32_e32 v153, 0x7fc00000
	v_mov_b32_e32 v154, 0xff800000
	v_mov_b32_e32 v155, 0x1600
	v_mov_b32_e32 v156, 0x1c00
	v_mov_b32_e32 v157, 0x41b17218
	v_not_b32_e32 v158, 63
	s_movk_i32 s65, 0x400
	s_movk_i32 s53, 0x1c00
	s_movk_i32 s66, 0x100
	s_mov_b32 s30, 0xffff
	s_mov_b32 s31, 0x3f317217
	s_mov_b32 s27, 0x7f800000
	s_mov_b32 s12, s28
	s_mov_b32 s95, 0
	s_mov_b64 s[22:23], 0x80
	s_mov_b32 s59, -1
	s_mov_b32 s61, -1
	v_writelane_b32 v247, s28, 44
	v_readlane_b32 s5, v248, 9
	v_readlane_b32 s9, v248, 45
	v_readlane_b32 s10, v248, 46
	v_readlane_b32 s11, v248, 47
	v_readlane_b32 s13, v248, 49
	v_readlane_b32 s18, v248, 54
	v_readlane_b32 s19, v248, 55
	v_readlane_b32 s20, v248, 56
	v_readlane_b32 s21, v248, 57
	v_writelane_b32 v247, s29, 45
	s_branch .LBB0_25
.Lexit_near:
	s_endpgm
.LBB0_23:
	s_or_b64 exec, exec, s[0:1]

; __device__ __forceinline__ unsigned pk2(float lo, float hi) { f32x2_t v = {lo, hi}; bf16x2_t b = __builtin_convertvector(v, bf16x2_t); return __builtin_bit_cast(unsigned, b); }
; __device__ __forceinline__ int transpose_tiles(int swave, const float* __restrict__ src, int lds_, int Kc, int Nc, bf16_t* __restrict__ dst, int ldd, char* shm, int job0, int bidx, int G) {
;     ...
;     const int nn = tid >> 3, k8 = (tid & 7) * 8;
;     if (n0 + nn < Nc) {
;       uint4 o;
;       o.x = pk2(tile[(k8 + 0) * 65 + nn], tile[(k8 + 1) * 65 + nn]);
;       o.y = pk2(tile[(k8 + 2) * 65 + nn], tile[(k8 + 3) * 65 + nn]);
;       o.z = pk2(tile[(k8 + 4) * 65 + nn], tile[(k8 + 5) * 65 + nn]);
;       o.w = pk2(tile[(k8 + 6) * 65 + nn], tile[(k8 + 7) * 65 + nn]);
;       *(uint4*)(dst + (size_t)(n0 + nn) * ldd + k0 + k8) = o;
;     }
.LBB0_559:
	s_ashr_i32 s8, s12, 31
	s_lshr_b32 s8, s8, 28
	s_add_i32 s8, s12, s8
	s_ashr_i32 s10, s8, 4
	s_waitcnt lgkmcnt(0)
	s_barrier
	v_lshl_add_u32 v14, s10, 6, v17
	s_movk_i32 s8, 0xd20
	v_cmp_gt_i32_e32 vcc, s8, v14
	s_and_saveexec_b64 s[8:9], vcc
	s_cbranch_execz .LBB0_554
	ds_read2_b32 v[20:21], v18 offset1:65
	ds_read2_b32 v[22:23], v18 offset0:130 offset1:195
	v_add_u32_e32 v13, 0x400, v18
	ds_read2_b32 v[24:25], v13 offset0:134 offset1:199
	s_lshl_b32 s10, s10, 10
	s_waitcnt lgkmcnt(2)
	v_cvt_pk_bf16_f32 v20, v20, v21
	s_waitcnt lgkmcnt(1)
	v_cvt_pk_bf16_f32 v21, v22, v23
	ds_read2_b32 v[22:23], v13 offset0:4 offset1:69
	v_ashrrev_i32_e32 v15, 31, v14
	s_sub_i32 s10, s13, s10
	v_lshlrev_b64 v[14:15], 11, v[14:15]
	v_lshl_add_u64 v[14:15], s[4:5], 0, v[14:15]
	s_ashr_i32 s11, s10, 31
	v_lshl_add_u64 v[14:15], s[10:11], 1, v[14:15]
	v_mov_b32_e32 v13, v3
	s_waitcnt lgkmcnt(0)
	v_cvt_pk_bf16_f32 v22, v22, v23
	v_cvt_pk_bf16_f32 v23, v24, v25
	v_lshl_add_u64 v[14:15], v[14:15], 0, v[12:13]
	global_store_dwordx4 v[14:15], v[20:23], off
	s_branch .LBB0_554
.Ltramp_23:
	s_branch .LBB0_23
.Ltramp_24:
	s_branch .LBB0_24
.LBB0_561:
	s_waitcnt lgkmcnt(0)
	s_barrier
	s_mov_b64 s[2:3], -1

; __device__ __forceinline__ uint4 ld_nt16(const void* p) { const u32x4_t t = __builtin_nontemporal_load((const u32x4_t*)p); return make_uint4(t[0], t[1], t[2], t[3]); }
; __device__ void conv_phase(int swave, const Params& p, int layer, int h) {
;     ...
;   for (int it = bidx * 512 + tidx; it < (TOK / 16) * NG; it += gridDim.x * 512) {
;     const int f8 = (it % NG) * 8, t0 = (it / NG) * 16, s0 = t0 & (SEQ - 1);
;     const int fa = FC0 + f8, fv = FFN + FC0 + f8;
;     float wa[3][8], wv[3][8], ba[8], bv[8];
; #pragma unroll
;     for (int tap = 0; tap < 3; ++tap) {
;       const float4 a0 = *(const float4*)(cw + tap * 5632 + fa), a1 = *(const float4*)(cw + tap * 5632 + fa + 4);
;       const float4 v0 = *(const float4*)(cw + tap * 5632 + fv), v1 = *(const float4*)(cw + tap * 5632 + fv + 4);
;       wa[tap][0] = a0.x; wa[tap][1] = a0.y; wa[tap][2] = a0.z; wa[tap][3] = a0.w; wa[tap][4] = a1.x; wa[tap][5] = a1.y; wa[tap][6] = a1.z; wa[tap][7] = a1.w;
;       wv[tap][0] = v0.x; wv[tap][1] = v0.y; wv[tap][2] = v0.z; wv[tap][3] = v0.w; wv[tap][4] = v1.x; wv[tap][5] = v1.y; wv[tap][6] = v1.z; wv[tap][7] = v1.w;
;     }
;     {
;       const float4 a0 = *(const float4*)(cb + fa), a1 = *(const float4*)(cb + fa + 4), v0 = *(const float4*)(cb + fv), v1 = *(const float4*)(cb + fv + 4);
;       ba[0] = a0.x; ba[1] = a0.y; ba[2] = a0.z; ba[3] = a0.w; ba[4] = a1.x; ba[5] = a1.y; ba[6] = a1.z; ba[7] = a1.w;
;       bv[0] = v0.x; bv[1] = v0.y; bv[2] = v0.z; bv[3] = v0.w; bv[4] = v1.x; bv[5] = v1.y; bv[6] = v1.z; bv[7] = v1.w;
;     }
;     const bf16_t* base = U + (size_t)t0 * ULD + f8;
;     const uint4 zero4 = make_uint4(0u, 0u, 0u, 0u);
;     uint4 pa = zero4, pv = zero4;
;     if (s0 > 0) { pa = ld_nt16(base - ULD); pv = ld_nt16(base - ULD + FFNH); }
;     uint4 ca = ld_nt16(base), cv = ld_nt16(base + FFNH);
; #pragma unroll 4
;     for (int i = 0; i < 16; ++i) {
;       uint4 na = zero4, nv = zero4;
;       if (s0 + i + 1 < SEQ) { na = ld_nt16(base + (size_t)(i + 1) * ULD); nv = ld_nt16(base + (size_t)(i + 1) * ULD + FFNH); }
.LBB0_708:
	v_mul_hi_u32 v0, v135, v142
	v_mul_lo_u32 v1, v0, s45
	v_sub_u32_e32 v1, v135, v1
	v_add_u32_e32 v2, 1, v0
	v_cmp_le_u32_e32 vcc, s45, v1
	s_lshl_b32 s24, s10, 5
	s_lshl_b32 s25, s10, 4
	v_cndmask_b32_e32 v0, v0, v2, vcc
	v_subrev_u32_e32 v2, s45, v1
	v_cndmask_b32_e32 v1, v1, v2, vcc
	v_add_u32_e32 v2, 1, v0
	v_cmp_le_u32_e32 vcc, s45, v1
	s_nop 1
	v_cndmask_b32_e32 v0, v0, v2, vcc
	v_mul_lo_u32 v1, v0, s45
	v_sub_u32_e32 v1, v135, v1
	v_lshlrev_b32_e32 v1, 3, v1
	v_add_u32_e32 v2, s35, v1
	v_lshlrev_b32_e32 v68, 2, v2
	v_add_u32_e32 v69, 0x2c00, v68
	global_load_dwordx4 v[4:7], v68, s[6:7] offset:16
	global_load_dwordx4 v[8:11], v68, s[6:7]
	global_load_dwordx4 v[12:15], v69, s[6:7] offset:16
	global_load_dwordx4 v[16:19], v69, s[6:7]
	global_load_dwordx4 v[20:23], v68, s[16:17] offset:16
	global_load_dwordx4 v[24:27], v68, s[16:17]
	global_load_dwordx4 v[28:31], v69, s[16:17] offset:16
	global_load_dwordx4 v[32:35], v69, s[16:17]
	global_load_dwordx4 v[36:39], v68, s[18:19] offset:16
	global_load_dwordx4 v[40:43], v68, s[18:19]
	global_load_dwordx4 v[44:47], v69, s[18:19] offset:16
	global_load_dwordx4 v[48:51], v69, s[18:19]
	global_load_dwordx4 v[52:55], v68, s[8:9] offset:16
	global_load_dwordx4 v[56:59], v68, s[8:9]
	global_load_dwordx4 v[60:63], v69, s[8:9] offset:16
	global_load_dwordx4 v[64:67], v69, s[8:9]
	v_lshlrev_b32_e32 v1, 1, v1
	v_mul_lo_u32 v2, v0, s24
	v_add_u32_e32 v2, v2, v1
	v_lshl_add_u64 v[68:69], s[4:5], 0, v[2:3]
	v_mul_lo_u32 v2, v0, s25
	v_add_u32_e32 v2, v2, v1
	v_lshl_add_u64 v[70:71], s[40:41], 0, v[2:3]
	v_lshl_add_u64 v[72:73], s[14:15], 1, v[68:69]
	v_and_b32_e32 v0, 0x7f, v0
	v_cmp_ne_u32_e64 s[2:3], 0, v0
	v_mov_b32_e32 v2, 0x7f
	v_cmp_ne_u32_e64 s[20:21], v0, v2
	global_load_dwordx4 v[160:163], v[72:73], off nt
	v_lshl_add_u64 v[72:73], v[72:73], 0, s[10:11]
	global_load_dwordx4 v[164:167], v[72:73], off nt
	v_lshl_add_u64 v[72:73], v[72:73], 0, s[10:11]
	global_load_dwordx4 v[168:171], v[72:73], off nt
	v_lshl_add_u64 v[72:73], v[72:73], 0, s[10:11]
	global_load_dwordx4 v[172:175], v[72:73], off nt
	v_lshl_add_u64 v[72:73], v[72:73], 0, s[10:11]
	global_load_dwordx4 v[176:179], v[72:73], off nt
	v_lshl_add_u64 v[72:73], v[72:73], 0, s[10:11]
	global_load_dwordx4 v[180:183], v[72:73], off nt
	v_lshl_add_u64 v[72:73], v[72:73], 0, s[10:11]
	global_load_dwordx4 v[184:187], v[72:73], off nt
	v_lshl_add_u64 v[72:73], v[72:73], 0, s[10:11]
	global_load_dwordx4 v[188:191], v[72:73], off nt
	v_lshl_add_u64 v[72:73], v[72:73], 0, s[10:11]
	global_load_dwordx4 v[192:195], v[72:73], off nt
	v_lshl_add_u64 v[72:73], v[72:73], 0, s[10:11]
	global_load_dwordx4 v[196:199], v[72:73], off nt
	v_lshl_add_u64 v[72:73], v[72:73], 0, s[10:11]
	global_load_dwordx4 v[200:203], v[72:73], off nt
	v_lshl_add_u64 v[72:73], v[72:73], 0, s[10:11]
	global_load_dwordx4 v[204:207], v[72:73], off nt
	v_lshl_add_u64 v[72:73], v[72:73], 0, s[10:11]
	global_load_dwordx4 v[208:211], v[72:73], off nt
	v_lshl_add_u64 v[72:73], v[72:73], 0, s[10:11]
	global_load_dwordx4 v[212:215], v[72:73], off nt
	v_lshl_add_u64 v[72:73], v[72:73], 0, s[10:11]
	global_load_dwordx4 v[216:219], v[72:73], off nt
	v_lshl_add_u64 v[72:73], v[72:73], 0, s[10:11]
	global_load_dwordx4 v[220:223], v[72:73], off nt
	v_lshl_add_u64 v[72:73], v[72:73], 0, s[10:11]
	global_load_dwordx4 v[224:227], v[72:73], off nt
	v_lshl_add_u64 v[72:73], v[72:73], 0, s[10:11]
	global_load_dwordx4 v[228:231], v[72:73], off nt
	v_lshl_add_u64 v[72:73], v[72:73], 0, s[10:11]
	global_load_dwordx4 v[232:235], v[72:73], off nt
	v_lshl_add_u64 v[72:73], v[72:73], 0, s[10:11]
	global_load_dwordx4 v[236:239], v[72:73], off nt
	v_lshl_add_u64 v[72:73], v[72:73], 0, s[10:11]
	s_waitcnt vmcnt(20)
	s_waitcnt vmcnt(18)
	v_cndmask_b32_e64 v160, 0, v160, s[2:3]
	v_cndmask_b32_e64 v161, 0, v161, s[2:3]
	v_cndmask_b32_e64 v162, 0, v162, s[2:3]
	v_cndmask_b32_e64 v163, 0, v163, s[2:3]
	v_cndmask_b32_e64 v164, 0, v164, s[2:3]
	v_cndmask_b32_e64 v165, 0, v165, s[2:3]
	v_cndmask_b32_e64 v166, 0, v166, s[2:3]
	v_cndmask_b32_e64 v167, 0, v167, s[2:3]
	v_lshlrev_b32_e32 v126, 16, v160
	v_and_b32_e32 v127, 0xffff0000, v160
	v_pk_fma_f32 v[74:75], v[8:9], v[126:127], v[56:57]
	v_lshlrev_b32_e32 v128, 16, v161
	v_and_b32_e32 v129, 0xffff0000, v161
	v_pk_fma_f32 v[76:77], v[10:11], v[128:129], v[58:59]
	v_lshlrev_b32_e32 v126, 16, v162
	v_and_b32_e32 v127, 0xffff0000, v162
	v_pk_fma_f32 v[78:79], v[4:5], v[126:127], v[52:53]
	v_lshlrev_b32_e32 v128, 16, v163
	v_and_b32_e32 v129, 0xffff0000, v163
	v_pk_fma_f32 v[80:81], v[6:7], v[128:129], v[54:55]
	v_lshlrev_b32_e32 v126, 16, v164
	v_and_b32_e32 v127, 0xffff0000, v164
	v_pk_fma_f32 v[82:83], v[16:17], v[126:127], v[64:65]
	v_lshlrev_b32_e32 v128, 16, v165
	v_and_b32_e32 v129, 0xffff0000, v165
	v_pk_fma_f32 v[84:85], v[18:19], v[128:129], v[66:67]
	v_lshlrev_b32_e32 v126, 16, v166
	v_and_b32_e32 v127, 0xffff0000, v166
	v_pk_fma_f32 v[86:87], v[12:13], v[126:127], v[60:61]
	v_lshlrev_b32_e32 v128, 16, v167
	v_and_b32_e32 v129, 0xffff0000, v167
	v_pk_fma_f32 v[88:89], v[14:15], v[128:129], v[62:63]
	global_load_dwordx4 v[160:163], v[72:73], off nt
	v_lshl_add_u64 v[72:73], v[72:73], 0, s[10:11]
	global_load_dwordx4 v[164:167], v[72:73], off nt
	v_lshl_add_u64 v[72:73], v[72:73], 0, s[10:11]
	s_waitcnt vmcnt(18)
; __device__ __forceinline__ uint4 ld_nt16(const void* p) { const u32x4_t t = __builtin_nontemporal_load((const u32x4_t*)p); return make_uint4(t[0], t[1], t[2], t[3]); }
; __device__ __forceinline__ unsigned pk2(float lo, float hi) { f32x2_t v = {lo, hi}; bf16x2_t b = __builtin_convertvector(v, bf16x2_t); return __builtin_bit_cast(unsigned, b); }
; __device__ __forceinline__ float lo_bf(unsigned u) { return __uint_as_float(u << 16); }
; __device__ __forceinline__ float hi_bf(unsigned u) { return __uint_as_float(u & 0xffff0000u); }
; __device__ __forceinline__ float siluf_(float x) { return x * __builtin_amdgcn_rcpf(1.f + __expf(-x)); }
; __device__ void conv_phase(int swave, const Params& p, int layer, int h) {
;     ...
;     for (int i = 0; i < 16; ++i) {
;       uint4 na = zero4, nv = zero4;
;       if (s0 + i + 1 < SEQ) { na = ld_nt16(base + (size_t)(i + 1) * ULD); nv = ld_nt16(base + (size_t)(i + 1) * ULD + FFNH); }
;       const unsigned rp[4] = {pa.x, pa.y, pa.z, pa.w}, rc[4] = {ca.x, ca.y, ca.z, ca.w}, rn[4] = {na.x, na.y, na.z, na.w};
;       const unsigned qp[4] = {pv.x, pv.y, pv.z, pv.w}, qc[4] = {cv.x, cv.y, cv.z, cv.w}, qn[4] = {nv.x, nv.y, nv.z, nv.w};
;       float oa[8], ov[8];
; #pragma unroll
;       for (int e = 0; e < 4; ++e) {
;         oa[2 * e] = ba[2 * e] + lo_bf(rp[e]) * wa[0][2 * e] + lo_bf(rc[e]) * wa[1][2 * e] + lo_bf(rn[e]) * wa[2][2 * e];
;         oa[2 * e + 1] = ba[2 * e + 1] + hi_bf(rp[e]) * wa[0][2 * e + 1] + hi_bf(rc[e]) * wa[1][2 * e + 1] + hi_bf(rn[e]) * wa[2][2 * e + 1];
;         ov[2 * e] = bv[2 * e] + lo_bf(qp[e]) * wv[0][2 * e] + lo_bf(qc[e]) * wv[1][2 * e] + lo_bf(qn[e]) * wv[2][2 * e];
;         ov[2 * e + 1] = bv[2 * e + 1] + hi_bf(qp[e]) * wv[0][2 * e + 1] + hi_bf(qc[e]) * wv[1][2 * e + 1] + hi_bf(qn[e]) * wv[2][2 * e + 1];
;       }
;       uint4 o;
;       o.x = pk2(siluf_(oa[0]) * ov[0], siluf_(oa[1]) * ov[1]); o.y = pk2(siluf_(oa[2]) * ov[2], siluf_(oa[3]) * ov[3]);
;       o.z = pk2(siluf_(oa[4]) * ov[4], siluf_(oa[5]) * ov[5]); o.w = pk2(siluf_(oa[6]) * ov[6], siluf_(oa[7]) * ov[7]);
;       *(uint4*)(ACT + (size_t)(t0 + i) * FFNH + f8) = o;
;       pa = ca; pv = cv; ca = na; cv = nv;
	v_lshlrev_b32_e32 v126, 16, v168
	v_and_b32_e32 v127, 0xffff0000, v168
	v_pk_fma_f32 v[90:91], v[8:9], v[126:127], v[56:57]
	v_pk_fma_f32 v[74:75], v[24:25], v[126:127], v[74:75]
	v_lshlrev_b32_e32 v128, 16, v169
	v_and_b32_e32 v129, 0xffff0000, v169
	v_pk_fma_f32 v[92:93], v[10:11], v[128:129], v[58:59]
	v_pk_fma_f32 v[76:77], v[26:27], v[128:129], v[76:77]
	v_lshlrev_b32_e32 v126, 16, v170
	v_and_b32_e32 v127, 0xffff0000, v170
	v_pk_fma_f32 v[94:95], v[4:5], v[126:127], v[52:53]
	v_pk_fma_f32 v[78:79], v[20:21], v[126:127], v[78:79]
	v_lshlrev_b32_e32 v128, 16, v171
	v_and_b32_e32 v129, 0xffff0000, v171
	v_pk_fma_f32 v[96:97], v[6:7], v[128:129], v[54:55]
	v_pk_fma_f32 v[80:81], v[22:23], v[128:129], v[80:81]
	v_lshlrev_b32_e32 v126, 16, v172
	v_and_b32_e32 v127, 0xffff0000, v172
	v_pk_fma_f32 v[98:99], v[16:17], v[126:127], v[64:65]
	v_pk_fma_f32 v[82:83], v[32:33], v[126:127], v[82:83]
	v_lshlrev_b32_e32 v128, 16, v173
	v_and_b32_e32 v129, 0xffff0000, v173
	v_pk_fma_f32 v[100:101], v[18:19], v[128:129], v[66:67]
	v_pk_fma_f32 v[84:85], v[34:35], v[128:129], v[84:85]
	v_lshlrev_b32_e32 v126, 16, v174
	v_and_b32_e32 v127, 0xffff0000, v174
	v_pk_fma_f32 v[102:103], v[12:13], v[126:127], v[60:61]
	v_pk_fma_f32 v[86:87], v[28:29], v[126:127], v[86:87]
	v_lshlrev_b32_e32 v128, 16, v175
	v_and_b32_e32 v129, 0xffff0000, v175
	v_pk_fma_f32 v[104:105], v[14:15], v[128:129], v[62:63]
	v_pk_fma_f32 v[88:89], v[30:31], v[128:129], v[88:89]
	global_load_dwordx4 v[168:171], v[72:73], off nt
	v_lshl_add_u64 v[72:73], v[72:73], 0, s[10:11]
	global_load_dwordx4 v[172:175], v[72:73], off nt
	v_lshl_add_u64 v[72:73], v[72:73], 0, s[10:11]
	s_waitcnt vmcnt(18)
	v_lshlrev_b32_e32 v126, 16, v176
	v_and_b32_e32 v127, 0xffff0000, v176
	v_pk_fma_f32 v[106:107], v[8:9], v[126:127], v[56:57]
	v_pk_fma_f32 v[90:91], v[24:25], v[126:127], v[90:91]
	v_pk_fma_f32 v[74:75], v[40:41], v[126:127], v[74:75]
	v_lshlrev_b32_e32 v128, 16, v177
	v_and_b32_e32 v129, 0xffff0000, v177
	v_pk_fma_f32 v[108:109], v[10:11], v[128:129], v[58:59]
	v_pk_fma_f32 v[92:93], v[26:27], v[128:129], v[92:93]
	v_pk_fma_f32 v[76:77], v[42:43], v[128:129], v[76:77]
	v_lshlrev_b32_e32 v126, 16, v178
	v_and_b32_e32 v127, 0xffff0000, v178
	v_pk_fma_f32 v[110:111], v[4:5], v[126:127], v[52:53]
	v_pk_fma_f32 v[94:95], v[20:21], v[126:127], v[94:95]
	v_pk_fma_f32 v[78:79], v[36:37], v[126:127], v[78:79]
	v_lshlrev_b32_e32 v128, 16, v179
	v_and_b32_e32 v129, 0xffff0000, v179
	v_pk_fma_f32 v[112:113], v[6:7], v[128:129], v[54:55]
	v_pk_fma_f32 v[96:97], v[22:23], v[128:129], v[96:97]
	v_pk_fma_f32 v[80:81], v[38:39], v[128:129], v[80:81]
	v_lshlrev_b32_e32 v126, 16, v180
	v_and_b32_e32 v127, 0xffff0000, v180
	v_pk_fma_f32 v[114:115], v[16:17], v[126:127], v[64:65]
	v_pk_fma_f32 v[98:99], v[32:33], v[126:127], v[98:99]
	v_pk_fma_f32 v[82:83], v[48:49], v[126:127], v[82:83]
	v_lshlrev_b32_e32 v128, 16, v181
	v_and_b32_e32 v129, 0xffff0000, v181
	v_pk_fma_f32 v[116:117], v[18:19], v[128:129], v[66:67]
	v_pk_fma_f32 v[100:101], v[34:35], v[128:129], v[100:101]
	v_pk_fma_f32 v[84:85], v[50:51], v[128:129], v[84:85]
	v_lshlrev_b32_e32 v126, 16, v182
	v_and_b32_e32 v127, 0xffff0000, v182
	v_pk_fma_f32 v[118:119], v[12:13], v[126:127], v[60:61]
	v_pk_fma_f32 v[102:103], v[28:29], v[126:127], v[102:103]
	v_pk_fma_f32 v[86:87], v[44:45], v[126:127], v[86:87]
	v_lshlrev_b32_e32 v128, 16, v183
	v_and_b32_e32 v129, 0xffff0000, v183
	v_pk_fma_f32 v[120:121], v[14:15], v[128:129], v[62:63]
	v_pk_fma_f32 v[104:105], v[30:31], v[128:129], v[104:105]
	v_pk_fma_f32 v[88:89], v[46:47], v[128:129], v[88:89]
	global_load_dwordx4 v[176:179], v[72:73], off nt
	v_lshl_add_u64 v[72:73], v[72:73], 0, s[10:11]
	global_load_dwordx4 v[180:183], v[72:73], off nt
	v_lshl_add_u64 v[72:73], v[72:73], 0, s[10:11]
	v_mul_f32_e32 v122, 0xbfb8aa3b, v74
	v_mul_f32_e32 v123, 0xbfb8aa3b, v75
	v_mul_f32_e32 v124, 0xbfb8aa3b, v76
	v_mul_f32_e32 v125, 0xbfb8aa3b, v77
	v_mul_f32_e32 v126, 0xbfb8aa3b, v78
	v_mul_f32_e32 v127, 0xbfb8aa3b, v79
	v_mul_f32_e32 v128, 0xbfb8aa3b, v80
	v_mul_f32_e32 v129, 0xbfb8aa3b, v81
	v_exp_f32_e32 v122, v122
	v_exp_f32_e32 v123, v123
	v_exp_f32_e32 v124, v124
	v_exp_f32_e32 v125, v125
	v_exp_f32_e32 v126, v126
	v_exp_f32_e32 v127, v127
	v_exp_f32_e32 v128, v128
	v_exp_f32_e32 v129, v129
	v_add_f32_e32 v122, 1.0, v122
	v_add_f32_e32 v123, 1.0, v123
	v_add_f32_e32 v124, 1.0, v124
	v_add_f32_e32 v125, 1.0, v125
	v_add_f32_e32 v126, 1.0, v126
	v_add_f32_e32 v127, 1.0, v127
	v_add_f32_e32 v128, 1.0, v128
	v_add_f32_e32 v129, 1.0, v129
	v_rcp_f32_e32 v122, v122
	v_rcp_f32_e32 v123, v123
	v_rcp_f32_e32 v124, v124
	v_rcp_f32_e32 v125, v125
	v_rcp_f32_e32 v126, v126
	v_rcp_f32_e32 v127, v127
	v_rcp_f32_e32 v128, v128
	v_rcp_f32_e32 v129, v129
	v_pk_mul_f32 v[74:75], v[74:75], v[122:123]
	v_pk_mul_f32 v[76:77], v[76:77], v[124:125]
	v_pk_mul_f32 v[78:79], v[78:79], v[126:127]
	v_pk_mul_f32 v[80:81], v[80:81], v[128:129]
	v_pk_mul_f32 v[74:75], v[82:83], v[74:75]
	v_pk_mul_f32 v[76:77], v[84:85], v[76:77]
	v_pk_mul_f32 v[78:79], v[86:87], v[78:79]
	v_pk_mul_f32 v[80:81], v[88:89], v[80:81]
	v_cvt_pk_bf16_f32 v138, v74, v75
	v_cvt_pk_bf16_f32 v139, v76, v77
	v_cvt_pk_bf16_f32 v140, v78, v79
	v_cvt_pk_bf16_f32 v141, v80, v81
	global_store_dwordx4 v[70:71], v[138:141], off
	v_lshl_add_u64 v[70:71], v[70:71], 0, s[10:11]
	s_waitcnt vmcnt(19)
; __device__ __forceinline__ uint4 ld_nt16(const void* p) { const u32x4_t t = __builtin_nontemporal_load((const u32x4_t*)p); return make_uint4(t[0], t[1], t[2], t[3]); }
; __device__ __forceinline__ unsigned pk2(float lo, float hi) { f32x2_t v = {lo, hi}; bf16x2_t b = __builtin_convertvector(v, bf16x2_t); return __builtin_bit_cast(unsigned, b); }
; __device__ __forceinline__ float lo_bf(unsigned u) { return __uint_as_float(u << 16); }
; __device__ __forceinline__ float hi_bf(unsigned u) { return __uint_as_float(u & 0xffff0000u); }
; __device__ __forceinline__ float siluf_(float x) { return x * __builtin_amdgcn_rcpf(1.f + __expf(-x)); }
; __device__ void conv_phase(int swave, const Params& p, int layer, int h) {
;     ...
;     for (int i = 0; i < 16; ++i) {
;       uint4 na = zero4, nv = zero4;
;       if (s0 + i + 1 < SEQ) { na = ld_nt16(base + (size_t)(i + 1) * ULD); nv = ld_nt16(base + (size_t)(i + 1) * ULD + FFNH); }
;       const unsigned rp[4] = {pa.x, pa.y, pa.z, pa.w}, rc[4] = {ca.x, ca.y, ca.z, ca.w}, rn[4] = {na.x, na.y, na.z, na.w};
;       const unsigned qp[4] = {pv.x, pv.y, pv.z, pv.w}, qc[4] = {cv.x, cv.y, cv.z, cv.w}, qn[4] = {nv.x, nv.y, nv.z, nv.w};
;       float oa[8], ov[8];
; #pragma unroll
;       for (int e = 0; e < 4; ++e) {
;         oa[2 * e] = ba[2 * e] + lo_bf(rp[e]) * wa[0][2 * e] + lo_bf(rc[e]) * wa[1][2 * e] + lo_bf(rn[e]) * wa[2][2 * e];
;         oa[2 * e + 1] = ba[2 * e + 1] + hi_bf(rp[e]) * wa[0][2 * e + 1] + hi_bf(rc[e]) * wa[1][2 * e + 1] + hi_bf(rn[e]) * wa[2][2 * e + 1];
;         ov[2 * e] = bv[2 * e] + lo_bf(qp[e]) * wv[0][2 * e] + lo_bf(qc[e]) * wv[1][2 * e] + lo_bf(qn[e]) * wv[2][2 * e];
;         ov[2 * e + 1] = bv[2 * e + 1] + hi_bf(qp[e]) * wv[0][2 * e + 1] + hi_bf(qc[e]) * wv[1][2 * e + 1] + hi_bf(qn[e]) * wv[2][2 * e + 1];
;       }
;       uint4 o;
;       o.x = pk2(siluf_(oa[0]) * ov[0], siluf_(oa[1]) * ov[1]); o.y = pk2(siluf_(oa[2]) * ov[2], siluf_(oa[3]) * ov[3]);
;       o.z = pk2(siluf_(oa[4]) * ov[4], siluf_(oa[5]) * ov[5]); o.w = pk2(siluf_(oa[6]) * ov[6], siluf_(oa[7]) * ov[7]);
;       *(uint4*)(ACT + (size_t)(t0 + i) * FFNH + f8) = o;
;       pa = ca; pv = cv; ca = na; cv = nv;
	v_lshlrev_b32_e32 v126, 16, v184
	v_and_b32_e32 v127, 0xffff0000, v184
	v_pk_fma_f32 v[74:75], v[8:9], v[126:127], v[56:57]
	v_pk_fma_f32 v[106:107], v[24:25], v[126:127], v[106:107]
	v_pk_fma_f32 v[90:91], v[40:41], v[126:127], v[90:91]
	v_lshlrev_b32_e32 v128, 16, v185
	v_and_b32_e32 v129, 0xffff0000, v185
	v_pk_fma_f32 v[76:77], v[10:11], v[128:129], v[58:59]
	v_pk_fma_f32 v[108:109], v[26:27], v[128:129], v[108:109]
	v_pk_fma_f32 v[92:93], v[42:43], v[128:129], v[92:93]
	v_lshlrev_b32_e32 v126, 16, v186
	v_and_b32_e32 v127, 0xffff0000, v186
	v_pk_fma_f32 v[78:79], v[4:5], v[126:127], v[52:53]
	v_pk_fma_f32 v[110:111], v[20:21], v[126:127], v[110:111]
	v_pk_fma_f32 v[94:95], v[36:37], v[126:127], v[94:95]
	v_lshlrev_b32_e32 v128, 16, v187
	v_and_b32_e32 v129, 0xffff0000, v187
	v_pk_fma_f32 v[80:81], v[6:7], v[128:129], v[54:55]
	v_pk_fma_f32 v[112:113], v[22:23], v[128:129], v[112:113]
	v_pk_fma_f32 v[96:97], v[38:39], v[128:129], v[96:97]
	v_lshlrev_b32_e32 v126, 16, v188
	v_and_b32_e32 v127, 0xffff0000, v188
	v_pk_fma_f32 v[82:83], v[16:17], v[126:127], v[64:65]
	v_pk_fma_f32 v[114:115], v[32:33], v[126:127], v[114:115]
	v_pk_fma_f32 v[98:99], v[48:49], v[126:127], v[98:99]
	v_lshlrev_b32_e32 v128, 16, v189
	v_and_b32_e32 v129, 0xffff0000, v189
	v_pk_fma_f32 v[84:85], v[18:19], v[128:129], v[66:67]
	v_pk_fma_f32 v[116:117], v[34:35], v[128:129], v[116:117]
	v_pk_fma_f32 v[100:101], v[50:51], v[128:129], v[100:101]
	v_lshlrev_b32_e32 v126, 16, v190
	v_and_b32_e32 v127, 0xffff0000, v190
	v_pk_fma_f32 v[86:87], v[12:13], v[126:127], v[60:61]
	v_pk_fma_f32 v[118:119], v[28:29], v[126:127], v[118:119]
	v_pk_fma_f32 v[102:103], v[44:45], v[126:127], v[102:103]
	v_lshlrev_b32_e32 v128, 16, v191
	v_and_b32_e32 v129, 0xffff0000, v191
	v_pk_fma_f32 v[88:89], v[14:15], v[128:129], v[62:63]
	v_pk_fma_f32 v[120:121], v[30:31], v[128:129], v[120:121]
	v_pk_fma_f32 v[104:105], v[46:47], v[128:129], v[104:105]
	global_load_dwordx4 v[184:187], v[72:73], off nt
	v_lshl_add_u64 v[72:73], v[72:73], 0, s[10:11]
	global_load_dwordx4 v[188:191], v[72:73], off nt
	v_lshl_add_u64 v[72:73], v[72:73], 0, s[10:11]
	v_mul_f32_e32 v122, 0xbfb8aa3b, v90
	v_mul_f32_e32 v123, 0xbfb8aa3b, v91
	v_mul_f32_e32 v124, 0xbfb8aa3b, v92
	v_mul_f32_e32 v125, 0xbfb8aa3b, v93
	v_mul_f32_e32 v126, 0xbfb8aa3b, v94
	v_mul_f32_e32 v127, 0xbfb8aa3b, v95
	v_mul_f32_e32 v128, 0xbfb8aa3b, v96
	v_mul_f32_e32 v129, 0xbfb8aa3b, v97
	v_exp_f32_e32 v122, v122
	v_exp_f32_e32 v123, v123
	v_exp_f32_e32 v124, v124
	v_exp_f32_e32 v125, v125
	v_exp_f32_e32 v126, v126
	v_exp_f32_e32 v127, v127
	v_exp_f32_e32 v128, v128
	v_exp_f32_e32 v129, v129
	v_add_f32_e32 v122, 1.0, v122
	v_add_f32_e32 v123, 1.0, v123
	v_add_f32_e32 v124, 1.0, v124
	v_add_f32_e32 v125, 1.0, v125
	v_add_f32_e32 v126, 1.0, v126
	v_add_f32_e32 v127, 1.0, v127
	v_add_f32_e32 v128, 1.0, v128
	v_add_f32_e32 v129, 1.0, v129
	v_rcp_f32_e32 v122, v122
	v_rcp_f32_e32 v123, v123
	v_rcp_f32_e32 v124, v124
	v_rcp_f32_e32 v125, v125
	v_rcp_f32_e32 v126, v126
	v_rcp_f32_e32 v127, v127
	v_rcp_f32_e32 v128, v128
	v_rcp_f32_e32 v129, v129
	v_pk_mul_f32 v[90:91], v[90:91], v[122:123]
	v_pk_mul_f32 v[92:93], v[92:93], v[124:125]
	v_pk_mul_f32 v[94:95], v[94:95], v[126:127]
	v_pk_mul_f32 v[96:97], v[96:97], v[128:129]
	v_pk_mul_f32 v[90:91], v[98:99], v[90:91]
	v_pk_mul_f32 v[92:93], v[100:101], v[92:93]
	v_pk_mul_f32 v[94:95], v[102:103], v[94:95]
	v_pk_mul_f32 v[96:97], v[104:105], v[96:97]
	v_cvt_pk_bf16_f32 v138, v90, v91
	v_cvt_pk_bf16_f32 v139, v92, v93
	v_cvt_pk_bf16_f32 v140, v94, v95
	v_cvt_pk_bf16_f32 v141, v96, v97
	global_store_dwordx4 v[70:71], v[138:141], off
	v_lshl_add_u64 v[70:71], v[70:71], 0, s[10:11]
	s_waitcnt vmcnt(20)
	v_lshlrev_b32_e32 v126, 16, v192
	v_and_b32_e32 v127, 0xffff0000, v192
	v_pk_fma_f32 v[90:91], v[8:9], v[126:127], v[56:57]
	v_pk_fma_f32 v[74:75], v[24:25], v[126:127], v[74:75]
	v_pk_fma_f32 v[106:107], v[40:41], v[126:127], v[106:107]
	v_lshlrev_b32_e32 v128, 16, v193
	v_and_b32_e32 v129, 0xffff0000, v193
	v_pk_fma_f32 v[92:93], v[10:11], v[128:129], v[58:59]
	v_pk_fma_f32 v[76:77], v[26:27], v[128:129], v[76:77]
	v_pk_fma_f32 v[108:109], v[42:43], v[128:129], v[108:109]
	v_lshlrev_b32_e32 v126, 16, v194
	v_and_b32_e32 v127, 0xffff0000, v194
	v_pk_fma_f32 v[94:95], v[4:5], v[126:127], v[52:53]
	v_pk_fma_f32 v[78:79], v[20:21], v[126:127], v[78:79]
	v_pk_fma_f32 v[110:111], v[36:37], v[126:127], v[110:111]
	v_lshlrev_b32_e32 v128, 16, v195
	v_and_b32_e32 v129, 0xffff0000, v195
	v_pk_fma_f32 v[96:97], v[6:7], v[128:129], v[54:55]
	v_pk_fma_f32 v[80:81], v[22:23], v[128:129], v[80:81]
	v_pk_fma_f32 v[112:113], v[38:39], v[128:129], v[112:113]
	v_lshlrev_b32_e32 v126, 16, v196
	v_and_b32_e32 v127, 0xffff0000, v196
	v_pk_fma_f32 v[98:99], v[16:17], v[126:127], v[64:65]
	v_pk_fma_f32 v[82:83], v[32:33], v[126:127], v[82:83]
	v_pk_fma_f32 v[114:115], v[48:49], v[126:127], v[114:115]
	v_lshlrev_b32_e32 v128, 16, v197
	v_and_b32_e32 v129, 0xffff0000, v197
	v_pk_fma_f32 v[100:101], v[18:19], v[128:129], v[66:67]
	v_pk_fma_f32 v[84:85], v[34:35], v[128:129], v[84:85]
	v_pk_fma_f32 v[116:117], v[50:51], v[128:129], v[116:117]
	v_lshlrev_b32_e32 v126, 16, v198
	v_and_b32_e32 v127, 0xffff0000, v198
	v_pk_fma_f32 v[102:103], v[12:13], v[126:127], v[60:61]
	v_pk_fma_f32 v[86:87], v[28:29], v[126:127], v[86:87]
	v_pk_fma_f32 v[118:119], v[44:45], v[126:127], v[118:119]
	v_lshlrev_b32_e32 v128, 16, v199
	v_and_b32_e32 v129, 0xffff0000, v199
	v_pk_fma_f32 v[104:105], v[14:15], v[128:129], v[62:63]
	v_pk_fma_f32 v[88:89], v[30:31], v[128:129], v[88:89]
	v_pk_fma_f32 v[120:121], v[46:47], v[128:129], v[120:121]
; __device__ __forceinline__ uint4 ld_nt16(const void* p) { const u32x4_t t = __builtin_nontemporal_load((const u32x4_t*)p); return make_uint4(t[0], t[1], t[2], t[3]); }
; __device__ __forceinline__ unsigned pk2(float lo, float hi) { f32x2_t v = {lo, hi}; bf16x2_t b = __builtin_convertvector(v, bf16x2_t); return __builtin_bit_cast(unsigned, b); }
; __device__ __forceinline__ float lo_bf(unsigned u) { return __uint_as_float(u << 16); }
; __device__ __forceinline__ float hi_bf(unsigned u) { return __uint_as_float(u & 0xffff0000u); }
; __device__ __forceinline__ float siluf_(float x) { return x * __builtin_amdgcn_rcpf(1.f + __expf(-x)); }
; __device__ void conv_phase(int swave, const Params& p, int layer, int h) {
;     ...
;     for (int i = 0; i < 16; ++i) {
;       uint4 na = zero4, nv = zero4;
;       if (s0 + i + 1 < SEQ) { na = ld_nt16(base + (size_t)(i + 1) * ULD); nv = ld_nt16(base + (size_t)(i + 1) * ULD + FFNH); }
;       const unsigned rp[4] = {pa.x, pa.y, pa.z, pa.w}, rc[4] = {ca.x, ca.y, ca.z, ca.w}, rn[4] = {na.x, na.y, na.z, na.w};
;       const unsigned qp[4] = {pv.x, pv.y, pv.z, pv.w}, qc[4] = {cv.x, cv.y, cv.z, cv.w}, qn[4] = {nv.x, nv.y, nv.z, nv.w};
;       float oa[8], ov[8];
; #pragma unroll
;       for (int e = 0; e < 4; ++e) {
;         oa[2 * e] = ba[2 * e] + lo_bf(rp[e]) * wa[0][2 * e] + lo_bf(rc[e]) * wa[1][2 * e] + lo_bf(rn[e]) * wa[2][2 * e];
;         oa[2 * e + 1] = ba[2 * e + 1] + hi_bf(rp[e]) * wa[0][2 * e + 1] + hi_bf(rc[e]) * wa[1][2 * e + 1] + hi_bf(rn[e]) * wa[2][2 * e + 1];
;         ov[2 * e] = bv[2 * e] + lo_bf(qp[e]) * wv[0][2 * e] + lo_bf(qc[e]) * wv[1][2 * e] + lo_bf(qn[e]) * wv[2][2 * e];
;         ov[2 * e + 1] = bv[2 * e + 1] + hi_bf(qp[e]) * wv[0][2 * e + 1] + hi_bf(qc[e]) * wv[1][2 * e + 1] + hi_bf(qn[e]) * wv[2][2 * e + 1];
;       }
;       uint4 o;
;       o.x = pk2(siluf_(oa[0]) * ov[0], siluf_(oa[1]) * ov[1]); o.y = pk2(siluf_(oa[2]) * ov[2], siluf_(oa[3]) * ov[3]);
;       o.z = pk2(siluf_(oa[4]) * ov[4], siluf_(oa[5]) * ov[5]); o.w = pk2(siluf_(oa[6]) * ov[6], siluf_(oa[7]) * ov[7]);
;       *(uint4*)(ACT + (size_t)(t0 + i) * FFNH + f8) = o;
;       pa = ca; pv = cv; ca = na; cv = nv;
	global_load_dwordx4 v[192:195], v[72:73], off nt
	v_lshl_add_u64 v[72:73], v[72:73], 0, s[10:11]
	global_load_dwordx4 v[196:199], v[72:73], off nt
	v_lshl_add_u64 v[72:73], v[72:73], 0, s[10:11]
	v_mul_f32_e32 v122, 0xbfb8aa3b, v106
	v_mul_f32_e32 v123, 0xbfb8aa3b, v107
	v_mul_f32_e32 v124, 0xbfb8aa3b, v108
	v_mul_f32_e32 v125, 0xbfb8aa3b, v109
	v_mul_f32_e32 v126, 0xbfb8aa3b, v110
	v_mul_f32_e32 v127, 0xbfb8aa3b, v111
	v_mul_f32_e32 v128, 0xbfb8aa3b, v112
	v_mul_f32_e32 v129, 0xbfb8aa3b, v113
	v_exp_f32_e32 v122, v122
	v_exp_f32_e32 v123, v123
	v_exp_f32_e32 v124, v124
	v_exp_f32_e32 v125, v125
	v_exp_f32_e32 v126, v126
	v_exp_f32_e32 v127, v127
	v_exp_f32_e32 v128, v128
	v_exp_f32_e32 v129, v129
	v_add_f32_e32 v122, 1.0, v122
	v_add_f32_e32 v123, 1.0, v123
	v_add_f32_e32 v124, 1.0, v124
	v_add_f32_e32 v125, 1.0, v125
	v_add_f32_e32 v126, 1.0, v126
	v_add_f32_e32 v127, 1.0, v127
	v_add_f32_e32 v128, 1.0, v128
	v_add_f32_e32 v129, 1.0, v129
	v_rcp_f32_e32 v122, v122
	v_rcp_f32_e32 v123, v123
	v_rcp_f32_e32 v124, v124
	v_rcp_f32_e32 v125, v125
	v_rcp_f32_e32 v126, v126
	v_rcp_f32_e32 v127, v127
	v_rcp_f32_e32 v128, v128
	v_rcp_f32_e32 v129, v129
	v_pk_mul_f32 v[106:107], v[106:107], v[122:123]
	v_pk_mul_f32 v[108:109], v[108:109], v[124:125]
	v_pk_mul_f32 v[110:111], v[110:111], v[126:127]
	v_pk_mul_f32 v[112:113], v[112:113], v[128:129]
	v_pk_mul_f32 v[106:107], v[114:115], v[106:107]
	v_pk_mul_f32 v[108:109], v[116:117], v[108:109]
	v_pk_mul_f32 v[110:111], v[118:119], v[110:111]
	v_pk_mul_f32 v[112:113], v[120:121], v[112:113]
	v_cvt_pk_bf16_f32 v138, v106, v107
	v_cvt_pk_bf16_f32 v139, v108, v109
	v_cvt_pk_bf16_f32 v140, v110, v111
	v_cvt_pk_bf16_f32 v141, v112, v113
	global_store_dwordx4 v[70:71], v[138:141], off
	v_lshl_add_u64 v[70:71], v[70:71], 0, s[10:11]
	s_waitcnt vmcnt(21)
	v_lshlrev_b32_e32 v126, 16, v200
	v_and_b32_e32 v127, 0xffff0000, v200
	v_pk_fma_f32 v[106:107], v[8:9], v[126:127], v[56:57]
	v_pk_fma_f32 v[90:91], v[24:25], v[126:127], v[90:91]
	v_pk_fma_f32 v[74:75], v[40:41], v[126:127], v[74:75]
	v_lshlrev_b32_e32 v128, 16, v201
	v_and_b32_e32 v129, 0xffff0000, v201
	v_pk_fma_f32 v[108:109], v[10:11], v[128:129], v[58:59]
	v_pk_fma_f32 v[92:93], v[26:27], v[128:129], v[92:93]
	v_pk_fma_f32 v[76:77], v[42:43], v[128:129], v[76:77]
	v_lshlrev_b32_e32 v126, 16, v202
	v_and_b32_e32 v127, 0xffff0000, v202
	v_pk_fma_f32 v[110:111], v[4:5], v[126:127], v[52:53]
	v_pk_fma_f32 v[94:95], v[20:21], v[126:127], v[94:95]
	v_pk_fma_f32 v[78:79], v[36:37], v[126:127], v[78:79]
	v_lshlrev_b32_e32 v128, 16, v203
	v_and_b32_e32 v129, 0xffff0000, v203
	v_pk_fma_f32 v[112:113], v[6:7], v[128:129], v[54:55]
	v_pk_fma_f32 v[96:97], v[22:23], v[128:129], v[96:97]
	v_pk_fma_f32 v[80:81], v[38:39], v[128:129], v[80:81]
	v_lshlrev_b32_e32 v126, 16, v204
	v_and_b32_e32 v127, 0xffff0000, v204
	v_pk_fma_f32 v[114:115], v[16:17], v[126:127], v[64:65]
	v_pk_fma_f32 v[98:99], v[32:33], v[126:127], v[98:99]
	v_pk_fma_f32 v[82:83], v[48:49], v[126:127], v[82:83]
	v_lshlrev_b32_e32 v128, 16, v205
	v_and_b32_e32 v129, 0xffff0000, v205
	v_pk_fma_f32 v[116:117], v[18:19], v[128:129], v[66:67]
	v_pk_fma_f32 v[100:101], v[34:35], v[128:129], v[100:101]
	v_pk_fma_f32 v[84:85], v[50:51], v[128:129], v[84:85]
	v_lshlrev_b32_e32 v126, 16, v206
	v_and_b32_e32 v127, 0xffff0000, v206
	v_pk_fma_f32 v[118:119], v[12:13], v[126:127], v[60:61]
	v_pk_fma_f32 v[102:103], v[28:29], v[126:127], v[102:103]
	v_pk_fma_f32 v[86:87], v[44:45], v[126:127], v[86:87]
	v_lshlrev_b32_e32 v128, 16, v207
	v_and_b32_e32 v129, 0xffff0000, v207
	v_pk_fma_f32 v[120:121], v[14:15], v[128:129], v[62:63]
	v_pk_fma_f32 v[104:105], v[30:31], v[128:129], v[104:105]
	v_pk_fma_f32 v[88:89], v[46:47], v[128:129], v[88:89]
	global_load_dwordx4 v[200:203], v[72:73], off nt
	v_lshl_add_u64 v[72:73], v[72:73], 0, s[10:11]
	global_load_dwordx4 v[204:207], v[72:73], off nt
	v_lshl_add_u64 v[72:73], v[72:73], 0, s[10:11]
	v_mul_f32_e32 v122, 0xbfb8aa3b, v74
	v_mul_f32_e32 v123, 0xbfb8aa3b, v75
	v_mul_f32_e32 v124, 0xbfb8aa3b, v76
	v_mul_f32_e32 v125, 0xbfb8aa3b, v77
	v_mul_f32_e32 v126, 0xbfb8aa3b, v78
	v_mul_f32_e32 v127, 0xbfb8aa3b, v79
	v_mul_f32_e32 v128, 0xbfb8aa3b, v80
	v_mul_f32_e32 v129, 0xbfb8aa3b, v81
	v_exp_f32_e32 v122, v122
	v_exp_f32_e32 v123, v123
	v_exp_f32_e32 v124, v124
	v_exp_f32_e32 v125, v125
	v_exp_f32_e32 v126, v126
	v_exp_f32_e32 v127, v127
	v_exp_f32_e32 v128, v128
	v_exp_f32_e32 v129, v129
	v_add_f32_e32 v122, 1.0, v122
	v_add_f32_e32 v123, 1.0, v123
	v_add_f32_e32 v124, 1.0, v124
	v_add_f32_e32 v125, 1.0, v125
	v_add_f32_e32 v126, 1.0, v126
	v_add_f32_e32 v127, 1.0, v127
	v_add_f32_e32 v128, 1.0, v128
	v_add_f32_e32 v129, 1.0, v129
	v_rcp_f32_e32 v122, v122
	v_rcp_f32_e32 v123, v123
	v_rcp_f32_e32 v124, v124
	v_rcp_f32_e32 v125, v125
	v_rcp_f32_e32 v126, v126
	v_rcp_f32_e32 v127, v127
	v_rcp_f32_e32 v128, v128
	v_rcp_f32_e32 v129, v129
	v_pk_mul_f32 v[74:75], v[74:75], v[122:123]
	v_pk_mul_f32 v[76:77], v[76:77], v[124:125]
	v_pk_mul_f32 v[78:79], v[78:79], v[126:127]
	v_pk_mul_f32 v[80:81], v[80:81], v[128:129]
	v_pk_mul_f32 v[74:75], v[82:83], v[74:75]
	v_pk_mul_f32 v[76:77], v[84:85], v[76:77]
	v_pk_mul_f32 v[78:79], v[86:87], v[78:79]
	v_pk_mul_f32 v[80:81], v[88:89], v[80:81]
	v_cvt_pk_bf16_f32 v138, v74, v75
	v_cvt_pk_bf16_f32 v139, v76, v77
	v_cvt_pk_bf16_f32 v140, v78, v79
	v_cvt_pk_bf16_f32 v141, v80, v81
	global_store_dwordx4 v[70:71], v[138:141], off
	v_lshl_add_u64 v[70:71], v[70:71], 0, s[10:11]
	s_waitcnt vmcnt(22)
; __device__ __forceinline__ uint4 ld_nt16(const void* p) { const u32x4_t t = __builtin_nontemporal_load((const u32x4_t*)p); return make_uint4(t[0], t[1], t[2], t[3]); }
; __device__ __forceinline__ unsigned pk2(float lo, float hi) { f32x2_t v = {lo, hi}; bf16x2_t b = __builtin_convertvector(v, bf16x2_t); return __builtin_bit_cast(unsigned, b); }
; __device__ __forceinline__ float lo_bf(unsigned u) { return __uint_as_float(u << 16); }
; __device__ __forceinline__ float hi_bf(unsigned u) { return __uint_as_float(u & 0xffff0000u); }
; __device__ __forceinline__ float siluf_(float x) { return x * __builtin_amdgcn_rcpf(1.f + __expf(-x)); }
; __device__ void conv_phase(int swave, const Params& p, int layer, int h) {
;     ...
;     for (int i = 0; i < 16; ++i) {
;       uint4 na = zero4, nv = zero4;
;       if (s0 + i + 1 < SEQ) { na = ld_nt16(base + (size_t)(i + 1) * ULD); nv = ld_nt16(base + (size_t)(i + 1) * ULD + FFNH); }
;       const unsigned rp[4] = {pa.x, pa.y, pa.z, pa.w}, rc[4] = {ca.x, ca.y, ca.z, ca.w}, rn[4] = {na.x, na.y, na.z, na.w};
;       const unsigned qp[4] = {pv.x, pv.y, pv.z, pv.w}, qc[4] = {cv.x, cv.y, cv.z, cv.w}, qn[4] = {nv.x, nv.y, nv.z, nv.w};
;       float oa[8], ov[8];
; #pragma unroll
;       for (int e = 0; e < 4; ++e) {
;         oa[2 * e] = ba[2 * e] + lo_bf(rp[e]) * wa[0][2 * e] + lo_bf(rc[e]) * wa[1][2 * e] + lo_bf(rn[e]) * wa[2][2 * e];
;         oa[2 * e + 1] = ba[2 * e + 1] + hi_bf(rp[e]) * wa[0][2 * e + 1] + hi_bf(rc[e]) * wa[1][2 * e + 1] + hi_bf(rn[e]) * wa[2][2 * e + 1];
;         ov[2 * e] = bv[2 * e] + lo_bf(qp[e]) * wv[0][2 * e] + lo_bf(qc[e]) * wv[1][2 * e] + lo_bf(qn[e]) * wv[2][2 * e];
;         ov[2 * e + 1] = bv[2 * e + 1] + hi_bf(qp[e]) * wv[0][2 * e + 1] + hi_bf(qc[e]) * wv[1][2 * e + 1] + hi_bf(qn[e]) * wv[2][2 * e + 1];
;       }
;       uint4 o;
;       o.x = pk2(siluf_(oa[0]) * ov[0], siluf_(oa[1]) * ov[1]); o.y = pk2(siluf_(oa[2]) * ov[2], siluf_(oa[3]) * ov[3]);
;       o.z = pk2(siluf_(oa[4]) * ov[4], siluf_(oa[5]) * ov[5]); o.w = pk2(siluf_(oa[6]) * ov[6], siluf_(oa[7]) * ov[7]);
;       *(uint4*)(ACT + (size_t)(t0 + i) * FFNH + f8) = o;
;       pa = ca; pv = cv; ca = na; cv = nv;
	v_lshlrev_b32_e32 v126, 16, v208
	v_and_b32_e32 v127, 0xffff0000, v208
	v_pk_fma_f32 v[74:75], v[8:9], v[126:127], v[56:57]
	v_pk_fma_f32 v[106:107], v[24:25], v[126:127], v[106:107]
	v_pk_fma_f32 v[90:91], v[40:41], v[126:127], v[90:91]
	v_lshlrev_b32_e32 v128, 16, v209
	v_and_b32_e32 v129, 0xffff0000, v209
	v_pk_fma_f32 v[76:77], v[10:11], v[128:129], v[58:59]
	v_pk_fma_f32 v[108:109], v[26:27], v[128:129], v[108:109]
	v_pk_fma_f32 v[92:93], v[42:43], v[128:129], v[92:93]
	v_lshlrev_b32_e32 v126, 16, v210
	v_and_b32_e32 v127, 0xffff0000, v210
	v_pk_fma_f32 v[78:79], v[4:5], v[126:127], v[52:53]
	v_pk_fma_f32 v[110:111], v[20:21], v[126:127], v[110:111]
	v_pk_fma_f32 v[94:95], v[36:37], v[126:127], v[94:95]
	v_lshlrev_b32_e32 v128, 16, v211
	v_and_b32_e32 v129, 0xffff0000, v211
	v_pk_fma_f32 v[80:81], v[6:7], v[128:129], v[54:55]
	v_pk_fma_f32 v[112:113], v[22:23], v[128:129], v[112:113]
	v_pk_fma_f32 v[96:97], v[38:39], v[128:129], v[96:97]
	v_lshlrev_b32_e32 v126, 16, v212
	v_and_b32_e32 v127, 0xffff0000, v212
	v_pk_fma_f32 v[82:83], v[16:17], v[126:127], v[64:65]
	v_pk_fma_f32 v[114:115], v[32:33], v[126:127], v[114:115]
	v_pk_fma_f32 v[98:99], v[48:49], v[126:127], v[98:99]
	v_lshlrev_b32_e32 v128, 16, v213
	v_and_b32_e32 v129, 0xffff0000, v213
	v_pk_fma_f32 v[84:85], v[18:19], v[128:129], v[66:67]
	v_pk_fma_f32 v[116:117], v[34:35], v[128:129], v[116:117]
	v_pk_fma_f32 v[100:101], v[50:51], v[128:129], v[100:101]
	v_lshlrev_b32_e32 v126, 16, v214
	v_and_b32_e32 v127, 0xffff0000, v214
	v_pk_fma_f32 v[86:87], v[12:13], v[126:127], v[60:61]
	v_pk_fma_f32 v[118:119], v[28:29], v[126:127], v[118:119]
	v_pk_fma_f32 v[102:103], v[44:45], v[126:127], v[102:103]
	v_lshlrev_b32_e32 v128, 16, v215
	v_and_b32_e32 v129, 0xffff0000, v215
	v_pk_fma_f32 v[88:89], v[14:15], v[128:129], v[62:63]
	v_pk_fma_f32 v[120:121], v[30:31], v[128:129], v[120:121]
	v_pk_fma_f32 v[104:105], v[46:47], v[128:129], v[104:105]
	global_load_dwordx4 v[208:211], v[72:73], off nt
	v_lshl_add_u64 v[72:73], v[72:73], 0, s[10:11]
	global_load_dwordx4 v[212:215], v[72:73], off nt
	v_lshl_add_u64 v[72:73], v[72:73], 0, s[10:11]
	v_mul_f32_e32 v122, 0xbfb8aa3b, v90
	v_mul_f32_e32 v123, 0xbfb8aa3b, v91
	v_mul_f32_e32 v124, 0xbfb8aa3b, v92
	v_mul_f32_e32 v125, 0xbfb8aa3b, v93
	v_mul_f32_e32 v126, 0xbfb8aa3b, v94
	v_mul_f32_e32 v127, 0xbfb8aa3b, v95
	v_mul_f32_e32 v128, 0xbfb8aa3b, v96
	v_mul_f32_e32 v129, 0xbfb8aa3b, v97
	v_exp_f32_e32 v122, v122
	v_exp_f32_e32 v123, v123
	v_exp_f32_e32 v124, v124
	v_exp_f32_e32 v125, v125
	v_exp_f32_e32 v126, v126
	v_exp_f32_e32 v127, v127
	v_exp_f32_e32 v128, v128
	v_exp_f32_e32 v129, v129
	v_add_f32_e32 v122, 1.0, v122
	v_add_f32_e32 v123, 1.0, v123
	v_add_f32_e32 v124, 1.0, v124
	v_add_f32_e32 v125, 1.0, v125
	v_add_f32_e32 v126, 1.0, v126
	v_add_f32_e32 v127, 1.0, v127
	v_add_f32_e32 v128, 1.0, v128
	v_add_f32_e32 v129, 1.0, v129
	v_rcp_f32_e32 v122, v122
	v_rcp_f32_e32 v123, v123
	v_rcp_f32_e32 v124, v124
	v_rcp_f32_e32 v125, v125
	v_rcp_f32_e32 v126, v126
	v_rcp_f32_e32 v127, v127
	v_rcp_f32_e32 v128, v128
	v_rcp_f32_e32 v129, v129
	v_pk_mul_f32 v[90:91], v[90:91], v[122:123]
	v_pk_mul_f32 v[92:93], v[92:93], v[124:125]
	v_pk_mul_f32 v[94:95], v[94:95], v[126:127]
	v_pk_mul_f32 v[96:97], v[96:97], v[128:129]
	v_pk_mul_f32 v[90:91], v[98:99], v[90:91]
	v_pk_mul_f32 v[92:93], v[100:101], v[92:93]
	v_pk_mul_f32 v[94:95], v[102:103], v[94:95]
	v_pk_mul_f32 v[96:97], v[104:105], v[96:97]
	v_cvt_pk_bf16_f32 v138, v90, v91
	v_cvt_pk_bf16_f32 v139, v92, v93
	v_cvt_pk_bf16_f32 v140, v94, v95
	v_cvt_pk_bf16_f32 v141, v96, v97
	global_store_dwordx4 v[70:71], v[138:141], off
	v_lshl_add_u64 v[70:71], v[70:71], 0, s[10:11]
	s_waitcnt vmcnt(23)
	v_lshlrev_b32_e32 v126, 16, v216
	v_and_b32_e32 v127, 0xffff0000, v216
	v_pk_fma_f32 v[90:91], v[8:9], v[126:127], v[56:57]
	v_pk_fma_f32 v[74:75], v[24:25], v[126:127], v[74:75]
	v_pk_fma_f32 v[106:107], v[40:41], v[126:127], v[106:107]
	v_lshlrev_b32_e32 v128, 16, v217
	v_and_b32_e32 v129, 0xffff0000, v217
	v_pk_fma_f32 v[92:93], v[10:11], v[128:129], v[58:59]
	v_pk_fma_f32 v[76:77], v[26:27], v[128:129], v[76:77]
	v_pk_fma_f32 v[108:109], v[42:43], v[128:129], v[108:109]
	v_lshlrev_b32_e32 v126, 16, v218
	v_and_b32_e32 v127, 0xffff0000, v218
	v_pk_fma_f32 v[94:95], v[4:5], v[126:127], v[52:53]
	v_pk_fma_f32 v[78:79], v[20:21], v[126:127], v[78:79]
	v_pk_fma_f32 v[110:111], v[36:37], v[126:127], v[110:111]
	v_lshlrev_b32_e32 v128, 16, v219
	v_and_b32_e32 v129, 0xffff0000, v219
	v_pk_fma_f32 v[96:97], v[6:7], v[128:129], v[54:55]
	v_pk_fma_f32 v[80:81], v[22:23], v[128:129], v[80:81]
	v_pk_fma_f32 v[112:113], v[38:39], v[128:129], v[112:113]
	v_lshlrev_b32_e32 v126, 16, v220
	v_and_b32_e32 v127, 0xffff0000, v220
	v_pk_fma_f32 v[98:99], v[16:17], v[126:127], v[64:65]
	v_pk_fma_f32 v[82:83], v[32:33], v[126:127], v[82:83]
	v_pk_fma_f32 v[114:115], v[48:49], v[126:127], v[114:115]
	v_lshlrev_b32_e32 v128, 16, v221
	v_and_b32_e32 v129, 0xffff0000, v221
	v_pk_fma_f32 v[100:101], v[18:19], v[128:129], v[66:67]
	v_pk_fma_f32 v[84:85], v[34:35], v[128:129], v[84:85]
	v_pk_fma_f32 v[116:117], v[50:51], v[128:129], v[116:117]
	v_lshlrev_b32_e32 v126, 16, v222
	v_and_b32_e32 v127, 0xffff0000, v222
	v_pk_fma_f32 v[102:103], v[12:13], v[126:127], v[60:61]
	v_pk_fma_f32 v[86:87], v[28:29], v[126:127], v[86:87]
	v_pk_fma_f32 v[118:119], v[44:45], v[126:127], v[118:119]
	v_lshlrev_b32_e32 v128, 16, v223
	v_and_b32_e32 v129, 0xffff0000, v223
	v_pk_fma_f32 v[104:105], v[14:15], v[128:129], v[62:63]
	v_pk_fma_f32 v[88:89], v[30:31], v[128:129], v[88:89]
	v_pk_fma_f32 v[120:121], v[46:47], v[128:129], v[120:121]
; __device__ __forceinline__ uint4 ld_nt16(const void* p) { const u32x4_t t = __builtin_nontemporal_load((const u32x4_t*)p); return make_uint4(t[0], t[1], t[2], t[3]); }
; __device__ __forceinline__ unsigned pk2(float lo, float hi) { f32x2_t v = {lo, hi}; bf16x2_t b = __builtin_convertvector(v, bf16x2_t); return __builtin_bit_cast(unsigned, b); }
; __device__ __forceinline__ float lo_bf(unsigned u) { return __uint_as_float(u << 16); }
; __device__ __forceinline__ float hi_bf(unsigned u) { return __uint_as_float(u & 0xffff0000u); }
; __device__ __forceinline__ float siluf_(float x) { return x * __builtin_amdgcn_rcpf(1.f + __expf(-x)); }
; __device__ void conv_phase(int swave, const Params& p, int layer, int h) {
;     ...
;     for (int i = 0; i < 16; ++i) {
;       uint4 na = zero4, nv = zero4;
;       if (s0 + i + 1 < SEQ) { na = ld_nt16(base + (size_t)(i + 1) * ULD); nv = ld_nt16(base + (size_t)(i + 1) * ULD + FFNH); }
;       const unsigned rp[4] = {pa.x, pa.y, pa.z, pa.w}, rc[4] = {ca.x, ca.y, ca.z, ca.w}, rn[4] = {na.x, na.y, na.z, na.w};
;       const unsigned qp[4] = {pv.x, pv.y, pv.z, pv.w}, qc[4] = {cv.x, cv.y, cv.z, cv.w}, qn[4] = {nv.x, nv.y, nv.z, nv.w};
;       float oa[8], ov[8];
; #pragma unroll
;       for (int e = 0; e < 4; ++e) {
;         oa[2 * e] = ba[2 * e] + lo_bf(rp[e]) * wa[0][2 * e] + lo_bf(rc[e]) * wa[1][2 * e] + lo_bf(rn[e]) * wa[2][2 * e];
;         oa[2 * e + 1] = ba[2 * e + 1] + hi_bf(rp[e]) * wa[0][2 * e + 1] + hi_bf(rc[e]) * wa[1][2 * e + 1] + hi_bf(rn[e]) * wa[2][2 * e + 1];
;         ov[2 * e] = bv[2 * e] + lo_bf(qp[e]) * wv[0][2 * e] + lo_bf(qc[e]) * wv[1][2 * e] + lo_bf(qn[e]) * wv[2][2 * e];
;         ov[2 * e + 1] = bv[2 * e + 1] + hi_bf(qp[e]) * wv[0][2 * e + 1] + hi_bf(qc[e]) * wv[1][2 * e + 1] + hi_bf(qn[e]) * wv[2][2 * e + 1];
;       }
;       uint4 o;
;       o.x = pk2(siluf_(oa[0]) * ov[0], siluf_(oa[1]) * ov[1]); o.y = pk2(siluf_(oa[2]) * ov[2], siluf_(oa[3]) * ov[3]);
;       o.z = pk2(siluf_(oa[4]) * ov[4], siluf_(oa[5]) * ov[5]); o.w = pk2(siluf_(oa[6]) * ov[6], siluf_(oa[7]) * ov[7]);
;       *(uint4*)(ACT + (size_t)(t0 + i) * FFNH + f8) = o;
;       pa = ca; pv = cv; ca = na; cv = nv;
	global_load_dwordx4 v[216:219], v[72:73], off nt
	v_lshl_add_u64 v[72:73], v[72:73], 0, s[10:11]
	global_load_dwordx4 v[220:223], v[72:73], off nt
	v_lshl_add_u64 v[72:73], v[72:73], 0, s[10:11]
	v_mul_f32_e32 v122, 0xbfb8aa3b, v106
	v_mul_f32_e32 v123, 0xbfb8aa3b, v107
	v_mul_f32_e32 v124, 0xbfb8aa3b, v108
	v_mul_f32_e32 v125, 0xbfb8aa3b, v109
	v_mul_f32_e32 v126, 0xbfb8aa3b, v110
	v_mul_f32_e32 v127, 0xbfb8aa3b, v111
	v_mul_f32_e32 v128, 0xbfb8aa3b, v112
	v_mul_f32_e32 v129, 0xbfb8aa3b, v113
	v_exp_f32_e32 v122, v122
	v_exp_f32_e32 v123, v123
	v_exp_f32_e32 v124, v124
	v_exp_f32_e32 v125, v125
	v_exp_f32_e32 v126, v126
	v_exp_f32_e32 v127, v127
	v_exp_f32_e32 v128, v128
	v_exp_f32_e32 v129, v129
	v_add_f32_e32 v122, 1.0, v122
	v_add_f32_e32 v123, 1.0, v123
	v_add_f32_e32 v124, 1.0, v124
	v_add_f32_e32 v125, 1.0, v125
	v_add_f32_e32 v126, 1.0, v126
	v_add_f32_e32 v127, 1.0, v127
	v_add_f32_e32 v128, 1.0, v128
	v_add_f32_e32 v129, 1.0, v129
	v_rcp_f32_e32 v122, v122
	v_rcp_f32_e32 v123, v123
	v_rcp_f32_e32 v124, v124
	v_rcp_f32_e32 v125, v125
	v_rcp_f32_e32 v126, v126
	v_rcp_f32_e32 v127, v127
	v_rcp_f32_e32 v128, v128
	v_rcp_f32_e32 v129, v129
	v_pk_mul_f32 v[106:107], v[106:107], v[122:123]
	v_pk_mul_f32 v[108:109], v[108:109], v[124:125]
	v_pk_mul_f32 v[110:111], v[110:111], v[126:127]
	v_pk_mul_f32 v[112:113], v[112:113], v[128:129]
	v_pk_mul_f32 v[106:107], v[114:115], v[106:107]
	v_pk_mul_f32 v[108:109], v[116:117], v[108:109]
	v_pk_mul_f32 v[110:111], v[118:119], v[110:111]
	v_pk_mul_f32 v[112:113], v[120:121], v[112:113]
	v_cvt_pk_bf16_f32 v138, v106, v107
	v_cvt_pk_bf16_f32 v139, v108, v109
	v_cvt_pk_bf16_f32 v140, v110, v111
	v_cvt_pk_bf16_f32 v141, v112, v113
	global_store_dwordx4 v[70:71], v[138:141], off
	v_lshl_add_u64 v[70:71], v[70:71], 0, s[10:11]
	s_waitcnt vmcnt(24)
	v_lshlrev_b32_e32 v126, 16, v224
	v_and_b32_e32 v127, 0xffff0000, v224
	v_pk_fma_f32 v[106:107], v[8:9], v[126:127], v[56:57]
	v_pk_fma_f32 v[90:91], v[24:25], v[126:127], v[90:91]
	v_pk_fma_f32 v[74:75], v[40:41], v[126:127], v[74:75]
	v_lshlrev_b32_e32 v128, 16, v225
	v_and_b32_e32 v129, 0xffff0000, v225
	v_pk_fma_f32 v[108:109], v[10:11], v[128:129], v[58:59]
	v_pk_fma_f32 v[92:93], v[26:27], v[128:129], v[92:93]
	v_pk_fma_f32 v[76:77], v[42:43], v[128:129], v[76:77]
	v_lshlrev_b32_e32 v126, 16, v226
	v_and_b32_e32 v127, 0xffff0000, v226
	v_pk_fma_f32 v[110:111], v[4:5], v[126:127], v[52:53]
	v_pk_fma_f32 v[94:95], v[20:21], v[126:127], v[94:95]
	v_pk_fma_f32 v[78:79], v[36:37], v[126:127], v[78:79]
	v_lshlrev_b32_e32 v128, 16, v227
	v_and_b32_e32 v129, 0xffff0000, v227
	v_pk_fma_f32 v[112:113], v[6:7], v[128:129], v[54:55]
	v_pk_fma_f32 v[96:97], v[22:23], v[128:129], v[96:97]
	v_pk_fma_f32 v[80:81], v[38:39], v[128:129], v[80:81]
	v_lshlrev_b32_e32 v126, 16, v228
	v_and_b32_e32 v127, 0xffff0000, v228
	v_pk_fma_f32 v[114:115], v[16:17], v[126:127], v[64:65]
	v_pk_fma_f32 v[98:99], v[32:33], v[126:127], v[98:99]
	v_pk_fma_f32 v[82:83], v[48:49], v[126:127], v[82:83]
	v_lshlrev_b32_e32 v128, 16, v229
	v_and_b32_e32 v129, 0xffff0000, v229
	v_pk_fma_f32 v[116:117], v[18:19], v[128:129], v[66:67]
	v_pk_fma_f32 v[100:101], v[34:35], v[128:129], v[100:101]
	v_pk_fma_f32 v[84:85], v[50:51], v[128:129], v[84:85]
	v_lshlrev_b32_e32 v126, 16, v230
	v_and_b32_e32 v127, 0xffff0000, v230
	v_pk_fma_f32 v[118:119], v[12:13], v[126:127], v[60:61]
	v_pk_fma_f32 v[102:103], v[28:29], v[126:127], v[102:103]
	v_pk_fma_f32 v[86:87], v[44:45], v[126:127], v[86:87]
	v_lshlrev_b32_e32 v128, 16, v231
	v_and_b32_e32 v129, 0xffff0000, v231
	v_pk_fma_f32 v[120:121], v[14:15], v[128:129], v[62:63]
	v_pk_fma_f32 v[104:105], v[30:31], v[128:129], v[104:105]
	v_pk_fma_f32 v[88:89], v[46:47], v[128:129], v[88:89]
	v_mul_f32_e32 v122, 0xbfb8aa3b, v74
	v_mul_f32_e32 v123, 0xbfb8aa3b, v75
	v_mul_f32_e32 v124, 0xbfb8aa3b, v76
	v_mul_f32_e32 v125, 0xbfb8aa3b, v77
	v_mul_f32_e32 v126, 0xbfb8aa3b, v78
	v_mul_f32_e32 v127, 0xbfb8aa3b, v79
	v_mul_f32_e32 v128, 0xbfb8aa3b, v80
	v_mul_f32_e32 v129, 0xbfb8aa3b, v81
	v_exp_f32_e32 v122, v122
	v_exp_f32_e32 v123, v123
	v_exp_f32_e32 v124, v124
	v_exp_f32_e32 v125, v125
	v_exp_f32_e32 v126, v126
	v_exp_f32_e32 v127, v127
	v_exp_f32_e32 v128, v128
	v_exp_f32_e32 v129, v129
	v_add_f32_e32 v122, 1.0, v122
	v_add_f32_e32 v123, 1.0, v123
	v_add_f32_e32 v124, 1.0, v124
	v_add_f32_e32 v125, 1.0, v125
	v_add_f32_e32 v126, 1.0, v126
	v_add_f32_e32 v127, 1.0, v127
	v_add_f32_e32 v128, 1.0, v128
	v_add_f32_e32 v129, 1.0, v129
	v_rcp_f32_e32 v122, v122
	v_rcp_f32_e32 v123, v123
	v_rcp_f32_e32 v124, v124
	v_rcp_f32_e32 v125, v125
	v_rcp_f32_e32 v126, v126
	v_rcp_f32_e32 v127, v127
	v_rcp_f32_e32 v128, v128
	v_rcp_f32_e32 v129, v129
	v_pk_mul_f32 v[74:75], v[74:75], v[122:123]
	v_pk_mul_f32 v[76:77], v[76:77], v[124:125]
	v_pk_mul_f32 v[78:79], v[78:79], v[126:127]
	v_pk_mul_f32 v[80:81], v[80:81], v[128:129]
	v_pk_mul_f32 v[74:75], v[82:83], v[74:75]
	v_pk_mul_f32 v[76:77], v[84:85], v[76:77]
	v_pk_mul_f32 v[78:79], v[86:87], v[78:79]
	v_pk_mul_f32 v[80:81], v[88:89], v[80:81]
	v_cvt_pk_bf16_f32 v138, v74, v75
	v_cvt_pk_bf16_f32 v139, v76, v77
	v_cvt_pk_bf16_f32 v140, v78, v79
	v_cvt_pk_bf16_f32 v141, v80, v81
	global_store_dwordx4 v[70:71], v[138:141], off
	v_lshl_add_u64 v[70:71], v[70:71], 0, s[10:11]
	s_waitcnt vmcnt(23)
; __device__ __forceinline__ uint4 ld_nt16(const void* p) { const u32x4_t t = __builtin_nontemporal_load((const u32x4_t*)p); return make_uint4(t[0], t[1], t[2], t[3]); }
; __device__ __forceinline__ unsigned pk2(float lo, float hi) { f32x2_t v = {lo, hi}; bf16x2_t b = __builtin_convertvector(v, bf16x2_t); return __builtin_bit_cast(unsigned, b); }
; __device__ __forceinline__ float lo_bf(unsigned u) { return __uint_as_float(u << 16); }
; __device__ __forceinline__ float hi_bf(unsigned u) { return __uint_as_float(u & 0xffff0000u); }
; __device__ __forceinline__ float siluf_(float x) { return x * __builtin_amdgcn_rcpf(1.f + __expf(-x)); }
; __device__ void conv_phase(int swave, const Params& p, int layer, int h) {
;     ...
;     for (int i = 0; i < 16; ++i) {
;       uint4 na = zero4, nv = zero4;
;       if (s0 + i + 1 < SEQ) { na = ld_nt16(base + (size_t)(i + 1) * ULD); nv = ld_nt16(base + (size_t)(i + 1) * ULD + FFNH); }
;       const unsigned rp[4] = {pa.x, pa.y, pa.z, pa.w}, rc[4] = {ca.x, ca.y, ca.z, ca.w}, rn[4] = {na.x, na.y, na.z, na.w};
;       const unsigned qp[4] = {pv.x, pv.y, pv.z, pv.w}, qc[4] = {cv.x, cv.y, cv.z, cv.w}, qn[4] = {nv.x, nv.y, nv.z, nv.w};
;       float oa[8], ov[8];
; #pragma unroll
;       for (int e = 0; e < 4; ++e) {
;         oa[2 * e] = ba[2 * e] + lo_bf(rp[e]) * wa[0][2 * e] + lo_bf(rc[e]) * wa[1][2 * e] + lo_bf(rn[e]) * wa[2][2 * e];
;         oa[2 * e + 1] = ba[2 * e + 1] + hi_bf(rp[e]) * wa[0][2 * e + 1] + hi_bf(rc[e]) * wa[1][2 * e + 1] + hi_bf(rn[e]) * wa[2][2 * e + 1];
;         ov[2 * e] = bv[2 * e] + lo_bf(qp[e]) * wv[0][2 * e] + lo_bf(qc[e]) * wv[1][2 * e] + lo_bf(qn[e]) * wv[2][2 * e];
;         ov[2 * e + 1] = bv[2 * e + 1] + hi_bf(qp[e]) * wv[0][2 * e + 1] + hi_bf(qc[e]) * wv[1][2 * e + 1] + hi_bf(qn[e]) * wv[2][2 * e + 1];
;       }
;       uint4 o;
;       o.x = pk2(siluf_(oa[0]) * ov[0], siluf_(oa[1]) * ov[1]); o.y = pk2(siluf_(oa[2]) * ov[2], siluf_(oa[3]) * ov[3]);
;       o.z = pk2(siluf_(oa[4]) * ov[4], siluf_(oa[5]) * ov[5]); o.w = pk2(siluf_(oa[6]) * ov[6], siluf_(oa[7]) * ov[7]);
;       *(uint4*)(ACT + (size_t)(t0 + i) * FFNH + f8) = o;
;       pa = ca; pv = cv; ca = na; cv = nv;
	v_lshlrev_b32_e32 v126, 16, v232
	v_and_b32_e32 v127, 0xffff0000, v232
	v_pk_fma_f32 v[74:75], v[8:9], v[126:127], v[56:57]
	v_pk_fma_f32 v[106:107], v[24:25], v[126:127], v[106:107]
	v_pk_fma_f32 v[90:91], v[40:41], v[126:127], v[90:91]
	v_lshlrev_b32_e32 v128, 16, v233
	v_and_b32_e32 v129, 0xffff0000, v233
	v_pk_fma_f32 v[76:77], v[10:11], v[128:129], v[58:59]
	v_pk_fma_f32 v[108:109], v[26:27], v[128:129], v[108:109]
	v_pk_fma_f32 v[92:93], v[42:43], v[128:129], v[92:93]
	v_lshlrev_b32_e32 v126, 16, v234
	v_and_b32_e32 v127, 0xffff0000, v234
	v_pk_fma_f32 v[78:79], v[4:5], v[126:127], v[52:53]
	v_pk_fma_f32 v[110:111], v[20:21], v[126:127], v[110:111]
	v_pk_fma_f32 v[94:95], v[36:37], v[126:127], v[94:95]
	v_lshlrev_b32_e32 v128, 16, v235
	v_and_b32_e32 v129, 0xffff0000, v235
	v_pk_fma_f32 v[80:81], v[6:7], v[128:129], v[54:55]
	v_pk_fma_f32 v[112:113], v[22:23], v[128:129], v[112:113]
	v_pk_fma_f32 v[96:97], v[38:39], v[128:129], v[96:97]
	v_lshlrev_b32_e32 v126, 16, v236
	v_and_b32_e32 v127, 0xffff0000, v236
	v_pk_fma_f32 v[82:83], v[16:17], v[126:127], v[64:65]
	v_pk_fma_f32 v[114:115], v[32:33], v[126:127], v[114:115]
	v_pk_fma_f32 v[98:99], v[48:49], v[126:127], v[98:99]
	v_lshlrev_b32_e32 v128, 16, v237
	v_and_b32_e32 v129, 0xffff0000, v237
	v_pk_fma_f32 v[84:85], v[18:19], v[128:129], v[66:67]
	v_pk_fma_f32 v[116:117], v[34:35], v[128:129], v[116:117]
	v_pk_fma_f32 v[100:101], v[50:51], v[128:129], v[100:101]
	v_lshlrev_b32_e32 v126, 16, v238
	v_and_b32_e32 v127, 0xffff0000, v238
	v_pk_fma_f32 v[86:87], v[12:13], v[126:127], v[60:61]
	v_pk_fma_f32 v[118:119], v[28:29], v[126:127], v[118:119]
	v_pk_fma_f32 v[102:103], v[44:45], v[126:127], v[102:103]
	v_lshlrev_b32_e32 v128, 16, v239
	v_and_b32_e32 v129, 0xffff0000, v239
	v_pk_fma_f32 v[88:89], v[14:15], v[128:129], v[62:63]
	v_pk_fma_f32 v[120:121], v[30:31], v[128:129], v[120:121]
	v_pk_fma_f32 v[104:105], v[46:47], v[128:129], v[104:105]
	v_mul_f32_e32 v122, 0xbfb8aa3b, v90
	v_mul_f32_e32 v123, 0xbfb8aa3b, v91
	v_mul_f32_e32 v124, 0xbfb8aa3b, v92
	v_mul_f32_e32 v125, 0xbfb8aa3b, v93
	v_mul_f32_e32 v126, 0xbfb8aa3b, v94
	v_mul_f32_e32 v127, 0xbfb8aa3b, v95
	v_mul_f32_e32 v128, 0xbfb8aa3b, v96
	v_mul_f32_e32 v129, 0xbfb8aa3b, v97
	v_exp_f32_e32 v122, v122
	v_exp_f32_e32 v123, v123
	v_exp_f32_e32 v124, v124
	v_exp_f32_e32 v125, v125
	v_exp_f32_e32 v126, v126
	v_exp_f32_e32 v127, v127
	v_exp_f32_e32 v128, v128
	v_exp_f32_e32 v129, v129
	v_add_f32_e32 v122, 1.0, v122
	v_add_f32_e32 v123, 1.0, v123
	v_add_f32_e32 v124, 1.0, v124
	v_add_f32_e32 v125, 1.0, v125
	v_add_f32_e32 v126, 1.0, v126
	v_add_f32_e32 v127, 1.0, v127
	v_add_f32_e32 v128, 1.0, v128
	v_add_f32_e32 v129, 1.0, v129
	v_rcp_f32_e32 v122, v122
	v_rcp_f32_e32 v123, v123
	v_rcp_f32_e32 v124, v124
	v_rcp_f32_e32 v125, v125
	v_rcp_f32_e32 v126, v126
	v_rcp_f32_e32 v127, v127
	v_rcp_f32_e32 v128, v128
	v_rcp_f32_e32 v129, v129
	v_pk_mul_f32 v[90:91], v[90:91], v[122:123]
	v_pk_mul_f32 v[92:93], v[92:93], v[124:125]
	v_pk_mul_f32 v[94:95], v[94:95], v[126:127]
	v_pk_mul_f32 v[96:97], v[96:97], v[128:129]
	v_pk_mul_f32 v[90:91], v[98:99], v[90:91]
	v_pk_mul_f32 v[92:93], v[100:101], v[92:93]
	v_pk_mul_f32 v[94:95], v[102:103], v[94:95]
	v_pk_mul_f32 v[96:97], v[104:105], v[96:97]
	v_cvt_pk_bf16_f32 v138, v90, v91
	v_cvt_pk_bf16_f32 v139, v92, v93
	v_cvt_pk_bf16_f32 v140, v94, v95
	v_cvt_pk_bf16_f32 v141, v96, v97
	global_store_dwordx4 v[70:71], v[138:141], off
	v_lshl_add_u64 v[70:71], v[70:71], 0, s[10:11]
	s_waitcnt vmcnt(22)
	v_lshlrev_b32_e32 v126, 16, v160
	v_and_b32_e32 v127, 0xffff0000, v160
	v_pk_fma_f32 v[90:91], v[8:9], v[126:127], v[56:57]
	v_pk_fma_f32 v[74:75], v[24:25], v[126:127], v[74:75]
	v_pk_fma_f32 v[106:107], v[40:41], v[126:127], v[106:107]
	v_lshlrev_b32_e32 v128, 16, v161
	v_and_b32_e32 v129, 0xffff0000, v161
	v_pk_fma_f32 v[92:93], v[10:11], v[128:129], v[58:59]
	v_pk_fma_f32 v[76:77], v[26:27], v[128:129], v[76:77]
	v_pk_fma_f32 v[108:109], v[42:43], v[128:129], v[108:109]
	v_lshlrev_b32_e32 v126, 16, v162
	v_and_b32_e32 v127, 0xffff0000, v162
	v_pk_fma_f32 v[94:95], v[4:5], v[126:127], v[52:53]
	v_pk_fma_f32 v[78:79], v[20:21], v[126:127], v[78:79]
	v_pk_fma_f32 v[110:111], v[36:37], v[126:127], v[110:111]
	v_lshlrev_b32_e32 v128, 16, v163
	v_and_b32_e32 v129, 0xffff0000, v163
	v_pk_fma_f32 v[96:97], v[6:7], v[128:129], v[54:55]
	v_pk_fma_f32 v[80:81], v[22:23], v[128:129], v[80:81]
	v_pk_fma_f32 v[112:113], v[38:39], v[128:129], v[112:113]
	v_lshlrev_b32_e32 v126, 16, v164
	v_and_b32_e32 v127, 0xffff0000, v164
	v_pk_fma_f32 v[98:99], v[16:17], v[126:127], v[64:65]
	v_pk_fma_f32 v[82:83], v[32:33], v[126:127], v[82:83]
	v_pk_fma_f32 v[114:115], v[48:49], v[126:127], v[114:115]
	v_lshlrev_b32_e32 v128, 16, v165
	v_and_b32_e32 v129, 0xffff0000, v165
	v_pk_fma_f32 v[100:101], v[18:19], v[128:129], v[66:67]
	v_pk_fma_f32 v[84:85], v[34:35], v[128:129], v[84:85]
	v_pk_fma_f32 v[116:117], v[50:51], v[128:129], v[116:117]
	v_lshlrev_b32_e32 v126, 16, v166
	v_and_b32_e32 v127, 0xffff0000, v166
	v_pk_fma_f32 v[102:103], v[12:13], v[126:127], v[60:61]
	v_pk_fma_f32 v[86:87], v[28:29], v[126:127], v[86:87]
	v_pk_fma_f32 v[118:119], v[44:45], v[126:127], v[118:119]
	v_lshlrev_b32_e32 v128, 16, v167
	v_and_b32_e32 v129, 0xffff0000, v167
	v_pk_fma_f32 v[104:105], v[14:15], v[128:129], v[62:63]
	v_pk_fma_f32 v[88:89], v[30:31], v[128:129], v[88:89]
	v_pk_fma_f32 v[120:121], v[46:47], v[128:129], v[120:121]
	v_mul_f32_e32 v122, 0xbfb8aa3b, v106
	v_mul_f32_e32 v123, 0xbfb8aa3b, v107
	v_mul_f32_e32 v124, 0xbfb8aa3b, v108
	v_mul_f32_e32 v125, 0xbfb8aa3b, v109
	v_mul_f32_e32 v126, 0xbfb8aa3b, v110
; __device__ __forceinline__ uint4 ld_nt16(const void* p) { const u32x4_t t = __builtin_nontemporal_load((const u32x4_t*)p); return make_uint4(t[0], t[1], t[2], t[3]); }
; __device__ __forceinline__ unsigned pk2(float lo, float hi) { f32x2_t v = {lo, hi}; bf16x2_t b = __builtin_convertvector(v, bf16x2_t); return __builtin_bit_cast(unsigned, b); }
; __device__ __forceinline__ float lo_bf(unsigned u) { return __uint_as_float(u << 16); }
; __device__ __forceinline__ float hi_bf(unsigned u) { return __uint_as_float(u & 0xffff0000u); }
; __device__ __forceinline__ float siluf_(float x) { return x * __builtin_amdgcn_rcpf(1.f + __expf(-x)); }
; __device__ void conv_phase(int swave, const Params& p, int layer, int h) {
;     ...
;     for (int i = 0; i < 16; ++i) {
;       uint4 na = zero4, nv = zero4;
;       if (s0 + i + 1 < SEQ) { na = ld_nt16(base + (size_t)(i + 1) * ULD); nv = ld_nt16(base + (size_t)(i + 1) * ULD + FFNH); }
;       const unsigned rp[4] = {pa.x, pa.y, pa.z, pa.w}, rc[4] = {ca.x, ca.y, ca.z, ca.w}, rn[4] = {na.x, na.y, na.z, na.w};
;       const unsigned qp[4] = {pv.x, pv.y, pv.z, pv.w}, qc[4] = {cv.x, cv.y, cv.z, cv.w}, qn[4] = {nv.x, nv.y, nv.z, nv.w};
;       float oa[8], ov[8];
; #pragma unroll
;       for (int e = 0; e < 4; ++e) {
;         oa[2 * e] = ba[2 * e] + lo_bf(rp[e]) * wa[0][2 * e] + lo_bf(rc[e]) * wa[1][2 * e] + lo_bf(rn[e]) * wa[2][2 * e];
;         oa[2 * e + 1] = ba[2 * e + 1] + hi_bf(rp[e]) * wa[0][2 * e + 1] + hi_bf(rc[e]) * wa[1][2 * e + 1] + hi_bf(rn[e]) * wa[2][2 * e + 1];
;         ov[2 * e] = bv[2 * e] + lo_bf(qp[e]) * wv[0][2 * e] + lo_bf(qc[e]) * wv[1][2 * e] + lo_bf(qn[e]) * wv[2][2 * e];
;         ov[2 * e + 1] = bv[2 * e + 1] + hi_bf(qp[e]) * wv[0][2 * e + 1] + hi_bf(qc[e]) * wv[1][2 * e + 1] + hi_bf(qn[e]) * wv[2][2 * e + 1];
;       }
;       uint4 o;
;       o.x = pk2(siluf_(oa[0]) * ov[0], siluf_(oa[1]) * ov[1]); o.y = pk2(siluf_(oa[2]) * ov[2], siluf_(oa[3]) * ov[3]);
;       o.z = pk2(siluf_(oa[4]) * ov[4], siluf_(oa[5]) * ov[5]); o.w = pk2(siluf_(oa[6]) * ov[6], siluf_(oa[7]) * ov[7]);
;       *(uint4*)(ACT + (size_t)(t0 + i) * FFNH + f8) = o;
;       pa = ca; pv = cv; ca = na; cv = nv;
	v_mul_f32_e32 v127, 0xbfb8aa3b, v111
	v_mul_f32_e32 v128, 0xbfb8aa3b, v112
	v_mul_f32_e32 v129, 0xbfb8aa3b, v113
	v_exp_f32_e32 v122, v122
	v_exp_f32_e32 v123, v123
	v_exp_f32_e32 v124, v124
	v_exp_f32_e32 v125, v125
	v_exp_f32_e32 v126, v126
	v_exp_f32_e32 v127, v127
	v_exp_f32_e32 v128, v128
	v_exp_f32_e32 v129, v129
	v_add_f32_e32 v122, 1.0, v122
	v_add_f32_e32 v123, 1.0, v123
	v_add_f32_e32 v124, 1.0, v124
	v_add_f32_e32 v125, 1.0, v125
	v_add_f32_e32 v126, 1.0, v126
	v_add_f32_e32 v127, 1.0, v127
	v_add_f32_e32 v128, 1.0, v128
	v_add_f32_e32 v129, 1.0, v129
	v_rcp_f32_e32 v122, v122
	v_rcp_f32_e32 v123, v123
	v_rcp_f32_e32 v124, v124
	v_rcp_f32_e32 v125, v125
	v_rcp_f32_e32 v126, v126
	v_rcp_f32_e32 v127, v127
	v_rcp_f32_e32 v128, v128
	v_rcp_f32_e32 v129, v129
	v_pk_mul_f32 v[106:107], v[106:107], v[122:123]
	v_pk_mul_f32 v[108:109], v[108:109], v[124:125]
	v_pk_mul_f32 v[110:111], v[110:111], v[126:127]
	v_pk_mul_f32 v[112:113], v[112:113], v[128:129]
	v_pk_mul_f32 v[106:107], v[114:115], v[106:107]
	v_pk_mul_f32 v[108:109], v[116:117], v[108:109]
	v_pk_mul_f32 v[110:111], v[118:119], v[110:111]
	v_pk_mul_f32 v[112:113], v[120:121], v[112:113]
	v_cvt_pk_bf16_f32 v138, v106, v107
	v_cvt_pk_bf16_f32 v139, v108, v109
	v_cvt_pk_bf16_f32 v140, v110, v111
	v_cvt_pk_bf16_f32 v141, v112, v113
	global_store_dwordx4 v[70:71], v[138:141], off
	v_lshl_add_u64 v[70:71], v[70:71], 0, s[10:11]
	s_waitcnt vmcnt(21)
	v_lshlrev_b32_e32 v126, 16, v168
	v_and_b32_e32 v127, 0xffff0000, v168
	v_pk_fma_f32 v[106:107], v[8:9], v[126:127], v[56:57]
	v_pk_fma_f32 v[90:91], v[24:25], v[126:127], v[90:91]
	v_pk_fma_f32 v[74:75], v[40:41], v[126:127], v[74:75]
	v_lshlrev_b32_e32 v128, 16, v169
	v_and_b32_e32 v129, 0xffff0000, v169
	v_pk_fma_f32 v[108:109], v[10:11], v[128:129], v[58:59]
	v_pk_fma_f32 v[92:93], v[26:27], v[128:129], v[92:93]
	v_pk_fma_f32 v[76:77], v[42:43], v[128:129], v[76:77]
	v_lshlrev_b32_e32 v126, 16, v170
	v_and_b32_e32 v127, 0xffff0000, v170
	v_pk_fma_f32 v[110:111], v[4:5], v[126:127], v[52:53]
	v_pk_fma_f32 v[94:95], v[20:21], v[126:127], v[94:95]
	v_pk_fma_f32 v[78:79], v[36:37], v[126:127], v[78:79]
	v_lshlrev_b32_e32 v128, 16, v171
	v_and_b32_e32 v129, 0xffff0000, v171
	v_pk_fma_f32 v[112:113], v[6:7], v[128:129], v[54:55]
	v_pk_fma_f32 v[96:97], v[22:23], v[128:129], v[96:97]
	v_pk_fma_f32 v[80:81], v[38:39], v[128:129], v[80:81]
	v_lshlrev_b32_e32 v126, 16, v172
	v_and_b32_e32 v127, 0xffff0000, v172
	v_pk_fma_f32 v[114:115], v[16:17], v[126:127], v[64:65]
	v_pk_fma_f32 v[98:99], v[32:33], v[126:127], v[98:99]
	v_pk_fma_f32 v[82:83], v[48:49], v[126:127], v[82:83]
	v_lshlrev_b32_e32 v128, 16, v173
	v_and_b32_e32 v129, 0xffff0000, v173
	v_pk_fma_f32 v[116:117], v[18:19], v[128:129], v[66:67]
	v_pk_fma_f32 v[100:101], v[34:35], v[128:129], v[100:101]
	v_pk_fma_f32 v[84:85], v[50:51], v[128:129], v[84:85]
	v_lshlrev_b32_e32 v126, 16, v174
	v_and_b32_e32 v127, 0xffff0000, v174
	v_pk_fma_f32 v[118:119], v[12:13], v[126:127], v[60:61]
	v_pk_fma_f32 v[102:103], v[28:29], v[126:127], v[102:103]
	v_pk_fma_f32 v[86:87], v[44:45], v[126:127], v[86:87]
	v_lshlrev_b32_e32 v128, 16, v175
	v_and_b32_e32 v129, 0xffff0000, v175
	v_pk_fma_f32 v[120:121], v[14:15], v[128:129], v[62:63]
	v_pk_fma_f32 v[104:105], v[30:31], v[128:129], v[104:105]
	v_pk_fma_f32 v[88:89], v[46:47], v[128:129], v[88:89]
	v_mul_f32_e32 v122, 0xbfb8aa3b, v74
	v_mul_f32_e32 v123, 0xbfb8aa3b, v75
	v_mul_f32_e32 v124, 0xbfb8aa3b, v76
	v_mul_f32_e32 v125, 0xbfb8aa3b, v77
	v_mul_f32_e32 v126, 0xbfb8aa3b, v78
	v_mul_f32_e32 v127, 0xbfb8aa3b, v79
	v_mul_f32_e32 v128, 0xbfb8aa3b, v80
	v_mul_f32_e32 v129, 0xbfb8aa3b, v81
	v_exp_f32_e32 v122, v122
	v_exp_f32_e32 v123, v123
	v_exp_f32_e32 v124, v124
	v_exp_f32_e32 v125, v125
	v_exp_f32_e32 v126, v126
	v_exp_f32_e32 v127, v127
	v_exp_f32_e32 v128, v128
	v_exp_f32_e32 v129, v129
	v_add_f32_e32 v122, 1.0, v122
	v_add_f32_e32 v123, 1.0, v123
	v_add_f32_e32 v124, 1.0, v124
	v_add_f32_e32 v125, 1.0, v125
	v_add_f32_e32 v126, 1.0, v126
	v_add_f32_e32 v127, 1.0, v127
	v_add_f32_e32 v128, 1.0, v128
	v_add_f32_e32 v129, 1.0, v129
	v_rcp_f32_e32 v122, v122
	v_rcp_f32_e32 v123, v123
	v_rcp_f32_e32 v124, v124
	v_rcp_f32_e32 v125, v125
	v_rcp_f32_e32 v126, v126
	v_rcp_f32_e32 v127, v127
	v_rcp_f32_e32 v128, v128
	v_rcp_f32_e32 v129, v129
	v_pk_mul_f32 v[74:75], v[74:75], v[122:123]
	v_pk_mul_f32 v[76:77], v[76:77], v[124:125]
	v_pk_mul_f32 v[78:79], v[78:79], v[126:127]
	v_pk_mul_f32 v[80:81], v[80:81], v[128:129]
	v_pk_mul_f32 v[74:75], v[82:83], v[74:75]
	v_pk_mul_f32 v[76:77], v[84:85], v[76:77]
	v_pk_mul_f32 v[78:79], v[86:87], v[78:79]
	v_pk_mul_f32 v[80:81], v[88:89], v[80:81]
	v_cvt_pk_bf16_f32 v138, v74, v75
	v_cvt_pk_bf16_f32 v139, v76, v77
	v_cvt_pk_bf16_f32 v140, v78, v79
	v_cvt_pk_bf16_f32 v141, v80, v81
	global_store_dwordx4 v[70:71], v[138:141], off
	v_lshl_add_u64 v[70:71], v[70:71], 0, s[10:11]
	s_waitcnt vmcnt(20)
; __device__ __forceinline__ uint4 ld_nt16(const void* p) { const u32x4_t t = __builtin_nontemporal_load((const u32x4_t*)p); return make_uint4(t[0], t[1], t[2], t[3]); }
; __device__ __forceinline__ unsigned pk2(float lo, float hi) { f32x2_t v = {lo, hi}; bf16x2_t b = __builtin_convertvector(v, bf16x2_t); return __builtin_bit_cast(unsigned, b); }
; __device__ __forceinline__ float lo_bf(unsigned u) { return __uint_as_float(u << 16); }
; __device__ __forceinline__ float hi_bf(unsigned u) { return __uint_as_float(u & 0xffff0000u); }
; __device__ __forceinline__ float siluf_(float x) { return x * __builtin_amdgcn_rcpf(1.f + __expf(-x)); }
; __device__ void conv_phase(int swave, const Params& p, int layer, int h) {
;     ...
;     for (int i = 0; i < 16; ++i) {
;       uint4 na = zero4, nv = zero4;
;       if (s0 + i + 1 < SEQ) { na = ld_nt16(base + (size_t)(i + 1) * ULD); nv = ld_nt16(base + (size_t)(i + 1) * ULD + FFNH); }
;       const unsigned rp[4] = {pa.x, pa.y, pa.z, pa.w}, rc[4] = {ca.x, ca.y, ca.z, ca.w}, rn[4] = {na.x, na.y, na.z, na.w};
;       const unsigned qp[4] = {pv.x, pv.y, pv.z, pv.w}, qc[4] = {cv.x, cv.y, cv.z, cv.w}, qn[4] = {nv.x, nv.y, nv.z, nv.w};
;       float oa[8], ov[8];
; #pragma unroll
;       for (int e = 0; e < 4; ++e) {
;         oa[2 * e] = ba[2 * e] + lo_bf(rp[e]) * wa[0][2 * e] + lo_bf(rc[e]) * wa[1][2 * e] + lo_bf(rn[e]) * wa[2][2 * e];
;         oa[2 * e + 1] = ba[2 * e + 1] + hi_bf(rp[e]) * wa[0][2 * e + 1] + hi_bf(rc[e]) * wa[1][2 * e + 1] + hi_bf(rn[e]) * wa[2][2 * e + 1];
;         ov[2 * e] = bv[2 * e] + lo_bf(qp[e]) * wv[0][2 * e] + lo_bf(qc[e]) * wv[1][2 * e] + lo_bf(qn[e]) * wv[2][2 * e];
;         ov[2 * e + 1] = bv[2 * e + 1] + hi_bf(qp[e]) * wv[0][2 * e + 1] + hi_bf(qc[e]) * wv[1][2 * e + 1] + hi_bf(qn[e]) * wv[2][2 * e + 1];
;       }
;       uint4 o;
;       o.x = pk2(siluf_(oa[0]) * ov[0], siluf_(oa[1]) * ov[1]); o.y = pk2(siluf_(oa[2]) * ov[2], siluf_(oa[3]) * ov[3]);
;       o.z = pk2(siluf_(oa[4]) * ov[4], siluf_(oa[5]) * ov[5]); o.w = pk2(siluf_(oa[6]) * ov[6], siluf_(oa[7]) * ov[7]);
;       *(uint4*)(ACT + (size_t)(t0 + i) * FFNH + f8) = o;
;       pa = ca; pv = cv; ca = na; cv = nv;
	v_lshlrev_b32_e32 v126, 16, v176
	v_and_b32_e32 v127, 0xffff0000, v176
	v_pk_fma_f32 v[74:75], v[8:9], v[126:127], v[56:57]
	v_pk_fma_f32 v[106:107], v[24:25], v[126:127], v[106:107]
	v_pk_fma_f32 v[90:91], v[40:41], v[126:127], v[90:91]
	v_lshlrev_b32_e32 v128, 16, v177
	v_and_b32_e32 v129, 0xffff0000, v177
	v_pk_fma_f32 v[76:77], v[10:11], v[128:129], v[58:59]
	v_pk_fma_f32 v[108:109], v[26:27], v[128:129], v[108:109]
	v_pk_fma_f32 v[92:93], v[42:43], v[128:129], v[92:93]
	v_lshlrev_b32_e32 v126, 16, v178
	v_and_b32_e32 v127, 0xffff0000, v178
	v_pk_fma_f32 v[78:79], v[4:5], v[126:127], v[52:53]
	v_pk_fma_f32 v[110:111], v[20:21], v[126:127], v[110:111]
	v_pk_fma_f32 v[94:95], v[36:37], v[126:127], v[94:95]
	v_lshlrev_b32_e32 v128, 16, v179
	v_and_b32_e32 v129, 0xffff0000, v179
	v_pk_fma_f32 v[80:81], v[6:7], v[128:129], v[54:55]
	v_pk_fma_f32 v[112:113], v[22:23], v[128:129], v[112:113]
	v_pk_fma_f32 v[96:97], v[38:39], v[128:129], v[96:97]
	v_lshlrev_b32_e32 v126, 16, v180
	v_and_b32_e32 v127, 0xffff0000, v180
	v_pk_fma_f32 v[82:83], v[16:17], v[126:127], v[64:65]
	v_pk_fma_f32 v[114:115], v[32:33], v[126:127], v[114:115]
	v_pk_fma_f32 v[98:99], v[48:49], v[126:127], v[98:99]
	v_lshlrev_b32_e32 v128, 16, v181
	v_and_b32_e32 v129, 0xffff0000, v181
	v_pk_fma_f32 v[84:85], v[18:19], v[128:129], v[66:67]
	v_pk_fma_f32 v[116:117], v[34:35], v[128:129], v[116:117]
	v_pk_fma_f32 v[100:101], v[50:51], v[128:129], v[100:101]
	v_lshlrev_b32_e32 v126, 16, v182
	v_and_b32_e32 v127, 0xffff0000, v182
	v_pk_fma_f32 v[86:87], v[12:13], v[126:127], v[60:61]
	v_pk_fma_f32 v[118:119], v[28:29], v[126:127], v[118:119]
	v_pk_fma_f32 v[102:103], v[44:45], v[126:127], v[102:103]
	v_lshlrev_b32_e32 v128, 16, v183
	v_and_b32_e32 v129, 0xffff0000, v183
	v_pk_fma_f32 v[88:89], v[14:15], v[128:129], v[62:63]
	v_pk_fma_f32 v[120:121], v[30:31], v[128:129], v[120:121]
	v_pk_fma_f32 v[104:105], v[46:47], v[128:129], v[104:105]
	v_mul_f32_e32 v122, 0xbfb8aa3b, v90
	v_mul_f32_e32 v123, 0xbfb8aa3b, v91
	v_mul_f32_e32 v124, 0xbfb8aa3b, v92
	v_mul_f32_e32 v125, 0xbfb8aa3b, v93
	v_mul_f32_e32 v126, 0xbfb8aa3b, v94
	v_mul_f32_e32 v127, 0xbfb8aa3b, v95
	v_mul_f32_e32 v128, 0xbfb8aa3b, v96
	v_mul_f32_e32 v129, 0xbfb8aa3b, v97
	v_exp_f32_e32 v122, v122
	v_exp_f32_e32 v123, v123
	v_exp_f32_e32 v124, v124
	v_exp_f32_e32 v125, v125
	v_exp_f32_e32 v126, v126
	v_exp_f32_e32 v127, v127
	v_exp_f32_e32 v128, v128
	v_exp_f32_e32 v129, v129
	v_add_f32_e32 v122, 1.0, v122
	v_add_f32_e32 v123, 1.0, v123
	v_add_f32_e32 v124, 1.0, v124
	v_add_f32_e32 v125, 1.0, v125
	v_add_f32_e32 v126, 1.0, v126
	v_add_f32_e32 v127, 1.0, v127
	v_add_f32_e32 v128, 1.0, v128
	v_add_f32_e32 v129, 1.0, v129
	v_rcp_f32_e32 v122, v122
	v_rcp_f32_e32 v123, v123
	v_rcp_f32_e32 v124, v124
	v_rcp_f32_e32 v125, v125
	v_rcp_f32_e32 v126, v126
	v_rcp_f32_e32 v127, v127
	v_rcp_f32_e32 v128, v128
	v_rcp_f32_e32 v129, v129
	v_pk_mul_f32 v[90:91], v[90:91], v[122:123]
	v_pk_mul_f32 v[92:93], v[92:93], v[124:125]
	v_pk_mul_f32 v[94:95], v[94:95], v[126:127]
	v_pk_mul_f32 v[96:97], v[96:97], v[128:129]
	v_pk_mul_f32 v[90:91], v[98:99], v[90:91]
	v_pk_mul_f32 v[92:93], v[100:101], v[92:93]
	v_pk_mul_f32 v[94:95], v[102:103], v[94:95]
	v_pk_mul_f32 v[96:97], v[104:105], v[96:97]
	v_cvt_pk_bf16_f32 v138, v90, v91
	v_cvt_pk_bf16_f32 v139, v92, v93
	v_cvt_pk_bf16_f32 v140, v94, v95
	v_cvt_pk_bf16_f32 v141, v96, v97
	global_store_dwordx4 v[70:71], v[138:141], off
	v_lshl_add_u64 v[70:71], v[70:71], 0, s[10:11]
	s_waitcnt vmcnt(18)
	v_lshlrev_b32_e32 v126, 16, v184
	v_and_b32_e32 v127, 0xffff0000, v184
	v_pk_fma_f32 v[90:91], v[8:9], v[126:127], v[56:57]
	v_pk_fma_f32 v[74:75], v[24:25], v[126:127], v[74:75]
	v_pk_fma_f32 v[106:107], v[40:41], v[126:127], v[106:107]
	v_lshlrev_b32_e32 v128, 16, v185
	v_and_b32_e32 v129, 0xffff0000, v185
	v_pk_fma_f32 v[92:93], v[10:11], v[128:129], v[58:59]
	v_pk_fma_f32 v[76:77], v[26:27], v[128:129], v[76:77]
	v_pk_fma_f32 v[108:109], v[42:43], v[128:129], v[108:109]
	v_lshlrev_b32_e32 v126, 16, v186
	v_and_b32_e32 v127, 0xffff0000, v186
	v_pk_fma_f32 v[94:95], v[4:5], v[126:127], v[52:53]
	v_pk_fma_f32 v[78:79], v[20:21], v[126:127], v[78:79]
	v_pk_fma_f32 v[110:111], v[36:37], v[126:127], v[110:111]
	v_lshlrev_b32_e32 v128, 16, v187
	v_and_b32_e32 v129, 0xffff0000, v187
	v_pk_fma_f32 v[96:97], v[6:7], v[128:129], v[54:55]
	v_pk_fma_f32 v[80:81], v[22:23], v[128:129], v[80:81]
	v_pk_fma_f32 v[112:113], v[38:39], v[128:129], v[112:113]
	v_lshlrev_b32_e32 v126, 16, v188
	v_and_b32_e32 v127, 0xffff0000, v188
	v_pk_fma_f32 v[98:99], v[16:17], v[126:127], v[64:65]
	v_pk_fma_f32 v[82:83], v[32:33], v[126:127], v[82:83]
	v_pk_fma_f32 v[114:115], v[48:49], v[126:127], v[114:115]
	v_lshlrev_b32_e32 v128, 16, v189
	v_and_b32_e32 v129, 0xffff0000, v189
	v_pk_fma_f32 v[100:101], v[18:19], v[128:129], v[66:67]
	v_pk_fma_f32 v[84:85], v[34:35], v[128:129], v[84:85]
	v_pk_fma_f32 v[116:117], v[50:51], v[128:129], v[116:117]
	v_lshlrev_b32_e32 v126, 16, v190
	v_and_b32_e32 v127, 0xffff0000, v190
	v_pk_fma_f32 v[102:103], v[12:13], v[126:127], v[60:61]
	v_pk_fma_f32 v[86:87], v[28:29], v[126:127], v[86:87]
	v_pk_fma_f32 v[118:119], v[44:45], v[126:127], v[118:119]
	v_lshlrev_b32_e32 v128, 16, v191
	v_and_b32_e32 v129, 0xffff0000, v191
	v_pk_fma_f32 v[104:105], v[14:15], v[128:129], v[62:63]
	v_pk_fma_f32 v[88:89], v[30:31], v[128:129], v[88:89]
	v_pk_fma_f32 v[120:121], v[46:47], v[128:129], v[120:121]
	v_mul_f32_e32 v122, 0xbfb8aa3b, v106
	v_mul_f32_e32 v123, 0xbfb8aa3b, v107
	v_mul_f32_e32 v124, 0xbfb8aa3b, v108
	v_mul_f32_e32 v125, 0xbfb8aa3b, v109
	v_mul_f32_e32 v126, 0xbfb8aa3b, v110
; __device__ __forceinline__ uint4 ld_nt16(const void* p) { const u32x4_t t = __builtin_nontemporal_load((const u32x4_t*)p); return make_uint4(t[0], t[1], t[2], t[3]); }
; __device__ __forceinline__ unsigned pk2(float lo, float hi) { f32x2_t v = {lo, hi}; bf16x2_t b = __builtin_convertvector(v, bf16x2_t); return __builtin_bit_cast(unsigned, b); }
; __device__ __forceinline__ float lo_bf(unsigned u) { return __uint_as_float(u << 16); }
; __device__ __forceinline__ float hi_bf(unsigned u) { return __uint_as_float(u & 0xffff0000u); }
; __device__ __forceinline__ float siluf_(float x) { return x * __builtin_amdgcn_rcpf(1.f + __expf(-x)); }
; __device__ void conv_phase(int swave, const Params& p, int layer, int h) {
;     ...
;     for (int i = 0; i < 16; ++i) {
;       uint4 na = zero4, nv = zero4;
;       if (s0 + i + 1 < SEQ) { na = ld_nt16(base + (size_t)(i + 1) * ULD); nv = ld_nt16(base + (size_t)(i + 1) * ULD + FFNH); }
;       const unsigned rp[4] = {pa.x, pa.y, pa.z, pa.w}, rc[4] = {ca.x, ca.y, ca.z, ca.w}, rn[4] = {na.x, na.y, na.z, na.w};
;       const unsigned qp[4] = {pv.x, pv.y, pv.z, pv.w}, qc[4] = {cv.x, cv.y, cv.z, cv.w}, qn[4] = {nv.x, nv.y, nv.z, nv.w};
;       float oa[8], ov[8];
; #pragma unroll
;       for (int e = 0; e < 4; ++e) {
;         oa[2 * e] = ba[2 * e] + lo_bf(rp[e]) * wa[0][2 * e] + lo_bf(rc[e]) * wa[1][2 * e] + lo_bf(rn[e]) * wa[2][2 * e];
;         oa[2 * e + 1] = ba[2 * e + 1] + hi_bf(rp[e]) * wa[0][2 * e + 1] + hi_bf(rc[e]) * wa[1][2 * e + 1] + hi_bf(rn[e]) * wa[2][2 * e + 1];
;         ov[2 * e] = bv[2 * e] + lo_bf(qp[e]) * wv[0][2 * e] + lo_bf(qc[e]) * wv[1][2 * e] + lo_bf(qn[e]) * wv[2][2 * e];
;         ov[2 * e + 1] = bv[2 * e + 1] + hi_bf(qp[e]) * wv[0][2 * e + 1] + hi_bf(qc[e]) * wv[1][2 * e + 1] + hi_bf(qn[e]) * wv[2][2 * e + 1];
;       }
;       uint4 o;
;       o.x = pk2(siluf_(oa[0]) * ov[0], siluf_(oa[1]) * ov[1]); o.y = pk2(siluf_(oa[2]) * ov[2], siluf_(oa[3]) * ov[3]);
;       o.z = pk2(siluf_(oa[4]) * ov[4], siluf_(oa[5]) * ov[5]); o.w = pk2(siluf_(oa[6]) * ov[6], siluf_(oa[7]) * ov[7]);
;       *(uint4*)(ACT + (size_t)(t0 + i) * FFNH + f8) = o;
;       pa = ca; pv = cv; ca = na; cv = nv;
	v_mul_f32_e32 v127, 0xbfb8aa3b, v111
	v_mul_f32_e32 v128, 0xbfb8aa3b, v112
	v_mul_f32_e32 v129, 0xbfb8aa3b, v113
	v_exp_f32_e32 v122, v122
	v_exp_f32_e32 v123, v123
	v_exp_f32_e32 v124, v124
	v_exp_f32_e32 v125, v125
	v_exp_f32_e32 v126, v126
	v_exp_f32_e32 v127, v127
	v_exp_f32_e32 v128, v128
	v_exp_f32_e32 v129, v129
	v_add_f32_e32 v122, 1.0, v122
	v_add_f32_e32 v123, 1.0, v123
	v_add_f32_e32 v124, 1.0, v124
	v_add_f32_e32 v125, 1.0, v125
	v_add_f32_e32 v126, 1.0, v126
	v_add_f32_e32 v127, 1.0, v127
	v_add_f32_e32 v128, 1.0, v128
	v_add_f32_e32 v129, 1.0, v129
	v_rcp_f32_e32 v122, v122
	v_rcp_f32_e32 v123, v123
	v_rcp_f32_e32 v124, v124
	v_rcp_f32_e32 v125, v125
	v_rcp_f32_e32 v126, v126
	v_rcp_f32_e32 v127, v127
	v_rcp_f32_e32 v128, v128
	v_rcp_f32_e32 v129, v129
	v_pk_mul_f32 v[106:107], v[106:107], v[122:123]
	v_pk_mul_f32 v[108:109], v[108:109], v[124:125]
	v_pk_mul_f32 v[110:111], v[110:111], v[126:127]
	v_pk_mul_f32 v[112:113], v[112:113], v[128:129]
	v_pk_mul_f32 v[106:107], v[114:115], v[106:107]
	v_pk_mul_f32 v[108:109], v[116:117], v[108:109]
	v_pk_mul_f32 v[110:111], v[118:119], v[110:111]
	v_pk_mul_f32 v[112:113], v[120:121], v[112:113]
	v_cvt_pk_bf16_f32 v138, v106, v107
	v_cvt_pk_bf16_f32 v139, v108, v109
	v_cvt_pk_bf16_f32 v140, v110, v111
	v_cvt_pk_bf16_f32 v141, v112, v113
	global_store_dwordx4 v[70:71], v[138:141], off
	v_lshl_add_u64 v[70:71], v[70:71], 0, s[10:11]
	s_waitcnt vmcnt(16)
	v_lshlrev_b32_e32 v126, 16, v192
	v_and_b32_e32 v127, 0xffff0000, v192
	v_pk_fma_f32 v[106:107], v[8:9], v[126:127], v[56:57]
	v_pk_fma_f32 v[90:91], v[24:25], v[126:127], v[90:91]
	v_pk_fma_f32 v[74:75], v[40:41], v[126:127], v[74:75]
	v_lshlrev_b32_e32 v128, 16, v193
	v_and_b32_e32 v129, 0xffff0000, v193
	v_pk_fma_f32 v[108:109], v[10:11], v[128:129], v[58:59]
	v_pk_fma_f32 v[92:93], v[26:27], v[128:129], v[92:93]
	v_pk_fma_f32 v[76:77], v[42:43], v[128:129], v[76:77]
	v_lshlrev_b32_e32 v126, 16, v194
	v_and_b32_e32 v127, 0xffff0000, v194
	v_pk_fma_f32 v[110:111], v[4:5], v[126:127], v[52:53]
	v_pk_fma_f32 v[94:95], v[20:21], v[126:127], v[94:95]
	v_pk_fma_f32 v[78:79], v[36:37], v[126:127], v[78:79]
	v_lshlrev_b32_e32 v128, 16, v195
	v_and_b32_e32 v129, 0xffff0000, v195
	v_pk_fma_f32 v[112:113], v[6:7], v[128:129], v[54:55]
	v_pk_fma_f32 v[96:97], v[22:23], v[128:129], v[96:97]
	v_pk_fma_f32 v[80:81], v[38:39], v[128:129], v[80:81]
	v_lshlrev_b32_e32 v126, 16, v196
	v_and_b32_e32 v127, 0xffff0000, v196
	v_pk_fma_f32 v[114:115], v[16:17], v[126:127], v[64:65]
	v_pk_fma_f32 v[98:99], v[32:33], v[126:127], v[98:99]
	v_pk_fma_f32 v[82:83], v[48:49], v[126:127], v[82:83]
	v_lshlrev_b32_e32 v128, 16, v197
	v_and_b32_e32 v129, 0xffff0000, v197
	v_pk_fma_f32 v[116:117], v[18:19], v[128:129], v[66:67]
	v_pk_fma_f32 v[100:101], v[34:35], v[128:129], v[100:101]
	v_pk_fma_f32 v[84:85], v[50:51], v[128:129], v[84:85]
	v_lshlrev_b32_e32 v126, 16, v198
	v_and_b32_e32 v127, 0xffff0000, v198
	v_pk_fma_f32 v[118:119], v[12:13], v[126:127], v[60:61]
	v_pk_fma_f32 v[102:103], v[28:29], v[126:127], v[102:103]
	v_pk_fma_f32 v[86:87], v[44:45], v[126:127], v[86:87]
	v_lshlrev_b32_e32 v128, 16, v199
	v_and_b32_e32 v129, 0xffff0000, v199
	v_pk_fma_f32 v[120:121], v[14:15], v[128:129], v[62:63]
	v_pk_fma_f32 v[104:105], v[30:31], v[128:129], v[104:105]
	v_pk_fma_f32 v[88:89], v[46:47], v[128:129], v[88:89]
	v_mul_f32_e32 v122, 0xbfb8aa3b, v74
	v_mul_f32_e32 v123, 0xbfb8aa3b, v75
	v_mul_f32_e32 v124, 0xbfb8aa3b, v76
	v_mul_f32_e32 v125, 0xbfb8aa3b, v77
	v_mul_f32_e32 v126, 0xbfb8aa3b, v78
	v_mul_f32_e32 v127, 0xbfb8aa3b, v79
	v_mul_f32_e32 v128, 0xbfb8aa3b, v80
	v_mul_f32_e32 v129, 0xbfb8aa3b, v81
	v_exp_f32_e32 v122, v122
	v_exp_f32_e32 v123, v123
	v_exp_f32_e32 v124, v124
	v_exp_f32_e32 v125, v125
	v_exp_f32_e32 v126, v126
	v_exp_f32_e32 v127, v127
	v_exp_f32_e32 v128, v128
	v_exp_f32_e32 v129, v129
	v_add_f32_e32 v122, 1.0, v122
	v_add_f32_e32 v123, 1.0, v123
	v_add_f32_e32 v124, 1.0, v124
	v_add_f32_e32 v125, 1.0, v125
	v_add_f32_e32 v126, 1.0, v126
	v_add_f32_e32 v127, 1.0, v127
	v_add_f32_e32 v128, 1.0, v128
	v_add_f32_e32 v129, 1.0, v129
	v_rcp_f32_e32 v122, v122
	v_rcp_f32_e32 v123, v123
	v_rcp_f32_e32 v124, v124
	v_rcp_f32_e32 v125, v125
	v_rcp_f32_e32 v126, v126
	v_rcp_f32_e32 v127, v127
	v_rcp_f32_e32 v128, v128
	v_rcp_f32_e32 v129, v129
	v_pk_mul_f32 v[74:75], v[74:75], v[122:123]
	v_pk_mul_f32 v[76:77], v[76:77], v[124:125]
	v_pk_mul_f32 v[78:79], v[78:79], v[126:127]
	v_pk_mul_f32 v[80:81], v[80:81], v[128:129]
	v_pk_mul_f32 v[74:75], v[82:83], v[74:75]
	v_pk_mul_f32 v[76:77], v[84:85], v[76:77]
	v_pk_mul_f32 v[78:79], v[86:87], v[78:79]
	v_pk_mul_f32 v[80:81], v[88:89], v[80:81]
	v_cvt_pk_bf16_f32 v138, v74, v75
	v_cvt_pk_bf16_f32 v139, v76, v77
	v_cvt_pk_bf16_f32 v140, v78, v79
	v_cvt_pk_bf16_f32 v141, v80, v81
	global_store_dwordx4 v[70:71], v[138:141], off
	v_lshl_add_u64 v[70:71], v[70:71], 0, s[10:11]
	s_waitcnt vmcnt(14)
; __device__ __forceinline__ uint4 ld_nt16(const void* p) { const u32x4_t t = __builtin_nontemporal_load((const u32x4_t*)p); return make_uint4(t[0], t[1], t[2], t[3]); }
; __device__ __forceinline__ unsigned pk2(float lo, float hi) { f32x2_t v = {lo, hi}; bf16x2_t b = __builtin_convertvector(v, bf16x2_t); return __builtin_bit_cast(unsigned, b); }
; __device__ __forceinline__ float lo_bf(unsigned u) { return __uint_as_float(u << 16); }
; __device__ __forceinline__ float hi_bf(unsigned u) { return __uint_as_float(u & 0xffff0000u); }
; __device__ __forceinline__ float siluf_(float x) { return x * __builtin_amdgcn_rcpf(1.f + __expf(-x)); }
; __device__ void conv_phase(int swave, const Params& p, int layer, int h) {
;     ...
;     for (int i = 0; i < 16; ++i) {
;       uint4 na = zero4, nv = zero4;
;       if (s0 + i + 1 < SEQ) { na = ld_nt16(base + (size_t)(i + 1) * ULD); nv = ld_nt16(base + (size_t)(i + 1) * ULD + FFNH); }
;       const unsigned rp[4] = {pa.x, pa.y, pa.z, pa.w}, rc[4] = {ca.x, ca.y, ca.z, ca.w}, rn[4] = {na.x, na.y, na.z, na.w};
;       const unsigned qp[4] = {pv.x, pv.y, pv.z, pv.w}, qc[4] = {cv.x, cv.y, cv.z, cv.w}, qn[4] = {nv.x, nv.y, nv.z, nv.w};
;       float oa[8], ov[8];
; #pragma unroll
;       for (int e = 0; e < 4; ++e) {
;         oa[2 * e] = ba[2 * e] + lo_bf(rp[e]) * wa[0][2 * e] + lo_bf(rc[e]) * wa[1][2 * e] + lo_bf(rn[e]) * wa[2][2 * e];
;         oa[2 * e + 1] = ba[2 * e + 1] + hi_bf(rp[e]) * wa[0][2 * e + 1] + hi_bf(rc[e]) * wa[1][2 * e + 1] + hi_bf(rn[e]) * wa[2][2 * e + 1];
;         ov[2 * e] = bv[2 * e] + lo_bf(qp[e]) * wv[0][2 * e] + lo_bf(qc[e]) * wv[1][2 * e] + lo_bf(qn[e]) * wv[2][2 * e];
;         ov[2 * e + 1] = bv[2 * e + 1] + hi_bf(qp[e]) * wv[0][2 * e + 1] + hi_bf(qc[e]) * wv[1][2 * e + 1] + hi_bf(qn[e]) * wv[2][2 * e + 1];
;       }
;       uint4 o;
;       o.x = pk2(siluf_(oa[0]) * ov[0], siluf_(oa[1]) * ov[1]); o.y = pk2(siluf_(oa[2]) * ov[2], siluf_(oa[3]) * ov[3]);
;       o.z = pk2(siluf_(oa[4]) * ov[4], siluf_(oa[5]) * ov[5]); o.w = pk2(siluf_(oa[6]) * ov[6], siluf_(oa[7]) * ov[7]);
;       *(uint4*)(ACT + (size_t)(t0 + i) * FFNH + f8) = o;
;       pa = ca; pv = cv; ca = na; cv = nv;
	v_lshlrev_b32_e32 v126, 16, v200
	v_and_b32_e32 v127, 0xffff0000, v200
	v_pk_fma_f32 v[74:75], v[8:9], v[126:127], v[56:57]
	v_pk_fma_f32 v[106:107], v[24:25], v[126:127], v[106:107]
	v_pk_fma_f32 v[90:91], v[40:41], v[126:127], v[90:91]
	v_lshlrev_b32_e32 v128, 16, v201
	v_and_b32_e32 v129, 0xffff0000, v201
	v_pk_fma_f32 v[76:77], v[10:11], v[128:129], v[58:59]
	v_pk_fma_f32 v[108:109], v[26:27], v[128:129], v[108:109]
	v_pk_fma_f32 v[92:93], v[42:43], v[128:129], v[92:93]
	v_lshlrev_b32_e32 v126, 16, v202
	v_and_b32_e32 v127, 0xffff0000, v202
	v_pk_fma_f32 v[78:79], v[4:5], v[126:127], v[52:53]
	v_pk_fma_f32 v[110:111], v[20:21], v[126:127], v[110:111]
	v_pk_fma_f32 v[94:95], v[36:37], v[126:127], v[94:95]
	v_lshlrev_b32_e32 v128, 16, v203
	v_and_b32_e32 v129, 0xffff0000, v203
	v_pk_fma_f32 v[80:81], v[6:7], v[128:129], v[54:55]
	v_pk_fma_f32 v[112:113], v[22:23], v[128:129], v[112:113]
	v_pk_fma_f32 v[96:97], v[38:39], v[128:129], v[96:97]
	v_lshlrev_b32_e32 v126, 16, v204
	v_and_b32_e32 v127, 0xffff0000, v204
	v_pk_fma_f32 v[82:83], v[16:17], v[126:127], v[64:65]
	v_pk_fma_f32 v[114:115], v[32:33], v[126:127], v[114:115]
	v_pk_fma_f32 v[98:99], v[48:49], v[126:127], v[98:99]
	v_lshlrev_b32_e32 v128, 16, v205
	v_and_b32_e32 v129, 0xffff0000, v205
	v_pk_fma_f32 v[84:85], v[18:19], v[128:129], v[66:67]
	v_pk_fma_f32 v[116:117], v[34:35], v[128:129], v[116:117]
	v_pk_fma_f32 v[100:101], v[50:51], v[128:129], v[100:101]
	v_lshlrev_b32_e32 v126, 16, v206
	v_and_b32_e32 v127, 0xffff0000, v206
	v_pk_fma_f32 v[86:87], v[12:13], v[126:127], v[60:61]
	v_pk_fma_f32 v[118:119], v[28:29], v[126:127], v[118:119]
	v_pk_fma_f32 v[102:103], v[44:45], v[126:127], v[102:103]
	v_lshlrev_b32_e32 v128, 16, v207
	v_and_b32_e32 v129, 0xffff0000, v207
	v_pk_fma_f32 v[88:89], v[14:15], v[128:129], v[62:63]
	v_pk_fma_f32 v[120:121], v[30:31], v[128:129], v[120:121]
	v_pk_fma_f32 v[104:105], v[46:47], v[128:129], v[104:105]
	v_mul_f32_e32 v122, 0xbfb8aa3b, v90
	v_mul_f32_e32 v123, 0xbfb8aa3b, v91
	v_mul_f32_e32 v124, 0xbfb8aa3b, v92
	v_mul_f32_e32 v125, 0xbfb8aa3b, v93
	v_mul_f32_e32 v126, 0xbfb8aa3b, v94
	v_mul_f32_e32 v127, 0xbfb8aa3b, v95
	v_mul_f32_e32 v128, 0xbfb8aa3b, v96
	v_mul_f32_e32 v129, 0xbfb8aa3b, v97
	v_exp_f32_e32 v122, v122
	v_exp_f32_e32 v123, v123
	v_exp_f32_e32 v124, v124
	v_exp_f32_e32 v125, v125
	v_exp_f32_e32 v126, v126
	v_exp_f32_e32 v127, v127
	v_exp_f32_e32 v128, v128
	v_exp_f32_e32 v129, v129
	v_add_f32_e32 v122, 1.0, v122
	v_add_f32_e32 v123, 1.0, v123
	v_add_f32_e32 v124, 1.0, v124
	v_add_f32_e32 v125, 1.0, v125
	v_add_f32_e32 v126, 1.0, v126
	v_add_f32_e32 v127, 1.0, v127
	v_add_f32_e32 v128, 1.0, v128
	v_add_f32_e32 v129, 1.0, v129
	v_rcp_f32_e32 v122, v122
	v_rcp_f32_e32 v123, v123
	v_rcp_f32_e32 v124, v124
	v_rcp_f32_e32 v125, v125
	v_rcp_f32_e32 v126, v126
	v_rcp_f32_e32 v127, v127
	v_rcp_f32_e32 v128, v128
	v_rcp_f32_e32 v129, v129
	v_pk_mul_f32 v[90:91], v[90:91], v[122:123]
	v_pk_mul_f32 v[92:93], v[92:93], v[124:125]
	v_pk_mul_f32 v[94:95], v[94:95], v[126:127]
	v_pk_mul_f32 v[96:97], v[96:97], v[128:129]
	v_pk_mul_f32 v[90:91], v[98:99], v[90:91]
	v_pk_mul_f32 v[92:93], v[100:101], v[92:93]
	v_pk_mul_f32 v[94:95], v[102:103], v[94:95]
	v_pk_mul_f32 v[96:97], v[104:105], v[96:97]
	v_cvt_pk_bf16_f32 v138, v90, v91
	v_cvt_pk_bf16_f32 v139, v92, v93
	v_cvt_pk_bf16_f32 v140, v94, v95
	v_cvt_pk_bf16_f32 v141, v96, v97
	global_store_dwordx4 v[70:71], v[138:141], off
	v_lshl_add_u64 v[70:71], v[70:71], 0, s[10:11]
	s_waitcnt vmcnt(12)
; __device__ __forceinline__ uint4 ld_nt16(const void* p) { const u32x4_t t = __builtin_nontemporal_load((const u32x4_t*)p); return make_uint4(t[0], t[1], t[2], t[3]); }
; __device__ __forceinline__ unsigned pk2(float lo, float hi) { f32x2_t v = {lo, hi}; bf16x2_t b = __builtin_convertvector(v, bf16x2_t); return __builtin_bit_cast(unsigned, b); }
; __device__ __forceinline__ float lo_bf(unsigned u) { return __uint_as_float(u << 16); }
; __device__ __forceinline__ float hi_bf(unsigned u) { return __uint_as_float(u & 0xffff0000u); }
; __device__ __forceinline__ float siluf_(float x) { return x * __builtin_amdgcn_rcpf(1.f + __expf(-x)); }
; __device__ void conv_phase(int swave, const Params& p, int layer, int h) {
;     ...
;     for (int i = 0; i < 16; ++i) {
;       uint4 na = zero4, nv = zero4;
;       if (s0 + i + 1 < SEQ) { na = ld_nt16(base + (size_t)(i + 1) * ULD); nv = ld_nt16(base + (size_t)(i + 1) * ULD + FFNH); }
;       const unsigned rp[4] = {pa.x, pa.y, pa.z, pa.w}, rc[4] = {ca.x, ca.y, ca.z, ca.w}, rn[4] = {na.x, na.y, na.z, na.w};
;       const unsigned qp[4] = {pv.x, pv.y, pv.z, pv.w}, qc[4] = {cv.x, cv.y, cv.z, cv.w}, qn[4] = {nv.x, nv.y, nv.z, nv.w};
;       float oa[8], ov[8];
; #pragma unroll
;       for (int e = 0; e < 4; ++e) {
;         oa[2 * e] = ba[2 * e] + lo_bf(rp[e]) * wa[0][2 * e] + lo_bf(rc[e]) * wa[1][2 * e] + lo_bf(rn[e]) * wa[2][2 * e];
;         oa[2 * e + 1] = ba[2 * e + 1] + hi_bf(rp[e]) * wa[0][2 * e + 1] + hi_bf(rc[e]) * wa[1][2 * e + 1] + hi_bf(rn[e]) * wa[2][2 * e + 1];
;         ov[2 * e] = bv[2 * e] + lo_bf(qp[e]) * wv[0][2 * e] + lo_bf(qc[e]) * wv[1][2 * e] + lo_bf(qn[e]) * wv[2][2 * e];
;         ov[2 * e + 1] = bv[2 * e + 1] + hi_bf(qp[e]) * wv[0][2 * e + 1] + hi_bf(qc[e]) * wv[1][2 * e + 1] + hi_bf(qn[e]) * wv[2][2 * e + 1];
;       }
;       uint4 o;
;       o.x = pk2(siluf_(oa[0]) * ov[0], siluf_(oa[1]) * ov[1]); o.y = pk2(siluf_(oa[2]) * ov[2], siluf_(oa[3]) * ov[3]);
;       o.z = pk2(siluf_(oa[4]) * ov[4], siluf_(oa[5]) * ov[5]); o.w = pk2(siluf_(oa[6]) * ov[6], siluf_(oa[7]) * ov[7]);
;       *(uint4*)(ACT + (size_t)(t0 + i) * FFNH + f8) = o;
;       pa = ca; pv = cv; ca = na; cv = nv;
	v_lshlrev_b32_e32 v126, 16, v208
	v_and_b32_e32 v127, 0xffff0000, v208
	v_pk_fma_f32 v[74:75], v[24:25], v[126:127], v[74:75]
	v_pk_fma_f32 v[106:107], v[40:41], v[126:127], v[106:107]
	v_lshlrev_b32_e32 v128, 16, v209
	v_and_b32_e32 v129, 0xffff0000, v209
	v_pk_fma_f32 v[76:77], v[26:27], v[128:129], v[76:77]
	v_pk_fma_f32 v[108:109], v[42:43], v[128:129], v[108:109]
	v_lshlrev_b32_e32 v126, 16, v210
	v_and_b32_e32 v127, 0xffff0000, v210
	v_pk_fma_f32 v[78:79], v[20:21], v[126:127], v[78:79]
	v_pk_fma_f32 v[110:111], v[36:37], v[126:127], v[110:111]
	v_lshlrev_b32_e32 v128, 16, v211
	v_and_b32_e32 v129, 0xffff0000, v211
	v_pk_fma_f32 v[80:81], v[22:23], v[128:129], v[80:81]
	v_pk_fma_f32 v[112:113], v[38:39], v[128:129], v[112:113]
	v_lshlrev_b32_e32 v126, 16, v212
	v_and_b32_e32 v127, 0xffff0000, v212
	v_pk_fma_f32 v[82:83], v[32:33], v[126:127], v[82:83]
	v_pk_fma_f32 v[114:115], v[48:49], v[126:127], v[114:115]
	v_lshlrev_b32_e32 v128, 16, v213
	v_and_b32_e32 v129, 0xffff0000, v213
	v_pk_fma_f32 v[84:85], v[34:35], v[128:129], v[84:85]
	v_pk_fma_f32 v[116:117], v[50:51], v[128:129], v[116:117]
	v_lshlrev_b32_e32 v126, 16, v214
	v_and_b32_e32 v127, 0xffff0000, v214
	v_pk_fma_f32 v[86:87], v[28:29], v[126:127], v[86:87]
	v_pk_fma_f32 v[118:119], v[44:45], v[126:127], v[118:119]
	v_lshlrev_b32_e32 v128, 16, v215
	v_and_b32_e32 v129, 0xffff0000, v215
	v_pk_fma_f32 v[88:89], v[30:31], v[128:129], v[88:89]
	v_pk_fma_f32 v[120:121], v[46:47], v[128:129], v[120:121]
	v_mul_f32_e32 v122, 0xbfb8aa3b, v106
	v_mul_f32_e32 v123, 0xbfb8aa3b, v107
	v_mul_f32_e32 v124, 0xbfb8aa3b, v108
	v_mul_f32_e32 v125, 0xbfb8aa3b, v109
	v_mul_f32_e32 v126, 0xbfb8aa3b, v110
	v_mul_f32_e32 v127, 0xbfb8aa3b, v111
	v_mul_f32_e32 v128, 0xbfb8aa3b, v112
	v_mul_f32_e32 v129, 0xbfb8aa3b, v113
	v_exp_f32_e32 v122, v122
	v_exp_f32_e32 v123, v123
	v_exp_f32_e32 v124, v124
	v_exp_f32_e32 v125, v125
	v_exp_f32_e32 v126, v126
	v_exp_f32_e32 v127, v127
	v_exp_f32_e32 v128, v128
	v_exp_f32_e32 v129, v129
	v_add_f32_e32 v122, 1.0, v122
	v_add_f32_e32 v123, 1.0, v123
	v_add_f32_e32 v124, 1.0, v124
	v_add_f32_e32 v125, 1.0, v125
	v_add_f32_e32 v126, 1.0, v126
	v_add_f32_e32 v127, 1.0, v127
	v_add_f32_e32 v128, 1.0, v128
	v_add_f32_e32 v129, 1.0, v129
	v_rcp_f32_e32 v122, v122
	v_rcp_f32_e32 v123, v123
	v_rcp_f32_e32 v124, v124
	v_rcp_f32_e32 v125, v125
	v_rcp_f32_e32 v126, v126
	v_rcp_f32_e32 v127, v127
	v_rcp_f32_e32 v128, v128
	v_rcp_f32_e32 v129, v129
	v_pk_mul_f32 v[106:107], v[106:107], v[122:123]
	v_pk_mul_f32 v[108:109], v[108:109], v[124:125]
	v_pk_mul_f32 v[110:111], v[110:111], v[126:127]
	v_pk_mul_f32 v[112:113], v[112:113], v[128:129]
	v_pk_mul_f32 v[106:107], v[114:115], v[106:107]
	v_pk_mul_f32 v[108:109], v[116:117], v[108:109]
	v_pk_mul_f32 v[110:111], v[118:119], v[110:111]
	v_pk_mul_f32 v[112:113], v[120:121], v[112:113]
	v_cvt_pk_bf16_f32 v138, v106, v107
	v_cvt_pk_bf16_f32 v139, v108, v109
	v_cvt_pk_bf16_f32 v140, v110, v111
	v_cvt_pk_bf16_f32 v141, v112, v113
	global_store_dwordx4 v[70:71], v[138:141], off
	v_lshl_add_u64 v[70:71], v[70:71], 0, s[10:11]
	s_waitcnt vmcnt(10)
	v_cndmask_b32_e64 v216, 0, v216, s[20:21]
	v_cndmask_b32_e64 v217, 0, v217, s[20:21]
	v_cndmask_b32_e64 v218, 0, v218, s[20:21]
	v_cndmask_b32_e64 v219, 0, v219, s[20:21]
	v_cndmask_b32_e64 v220, 0, v220, s[20:21]
	v_cndmask_b32_e64 v221, 0, v221, s[20:21]
	v_cndmask_b32_e64 v222, 0, v222, s[20:21]
	v_cndmask_b32_e64 v223, 0, v223, s[20:21]
	v_lshlrev_b32_e32 v126, 16, v216
	v_and_b32_e32 v127, 0xffff0000, v216
	v_pk_fma_f32 v[74:75], v[40:41], v[126:127], v[74:75]
	v_lshlrev_b32_e32 v128, 16, v217
	v_and_b32_e32 v129, 0xffff0000, v217
	v_pk_fma_f32 v[76:77], v[42:43], v[128:129], v[76:77]
	v_lshlrev_b32_e32 v126, 16, v218
	v_and_b32_e32 v127, 0xffff0000, v218
	v_pk_fma_f32 v[78:79], v[36:37], v[126:127], v[78:79]
	v_lshlrev_b32_e32 v128, 16, v219
	v_and_b32_e32 v129, 0xffff0000, v219
	v_pk_fma_f32 v[80:81], v[38:39], v[128:129], v[80:81]
	v_lshlrev_b32_e32 v126, 16, v220
	v_and_b32_e32 v127, 0xffff0000, v220
	v_pk_fma_f32 v[82:83], v[48:49], v[126:127], v[82:83]
	v_lshlrev_b32_e32 v128, 16, v221
	v_and_b32_e32 v129, 0xffff0000, v221
	v_pk_fma_f32 v[84:85], v[50:51], v[128:129], v[84:85]
	v_lshlrev_b32_e32 v126, 16, v222
	v_and_b32_e32 v127, 0xffff0000, v222
	v_pk_fma_f32 v[86:87], v[44:45], v[126:127], v[86:87]
	v_lshlrev_b32_e32 v128, 16, v223
	v_and_b32_e32 v129, 0xffff0000, v223
	v_pk_fma_f32 v[88:89], v[46:47], v[128:129], v[88:89]
	v_mul_f32_e32 v122, 0xbfb8aa3b, v74
	v_mul_f32_e32 v123, 0xbfb8aa3b, v75
	v_mul_f32_e32 v124, 0xbfb8aa3b, v76
	v_mul_f32_e32 v125, 0xbfb8aa3b, v77
	v_mul_f32_e32 v126, 0xbfb8aa3b, v78
	v_mul_f32_e32 v127, 0xbfb8aa3b, v79
	v_mul_f32_e32 v128, 0xbfb8aa3b, v80
	v_mul_f32_e32 v129, 0xbfb8aa3b, v81
	v_exp_f32_e32 v122, v122
	v_exp_f32_e32 v123, v123
	v_exp_f32_e32 v124, v124
	v_exp_f32_e32 v125, v125
	v_exp_f32_e32 v126, v126
	v_exp_f32_e32 v127, v127
	v_exp_f32_e32 v128, v128
	v_exp_f32_e32 v129, v129
	v_add_f32_e32 v122, 1.0, v122
	v_add_f32_e32 v123, 1.0, v123
	v_add_f32_e32 v124, 1.0, v124
	v_add_f32_e32 v125, 1.0, v125
	v_add_f32_e32 v126, 1.0, v126
	v_add_f32_e32 v127, 1.0, v127
	v_add_f32_e32 v128, 1.0, v128
	v_add_f32_e32 v129, 1.0, v129
	v_rcp_f32_e32 v122, v122
	v_rcp_f32_e32 v123, v123
	v_rcp_f32_e32 v124, v124
	v_rcp_f32_e32 v125, v125
	v_rcp_f32_e32 v126, v126
	v_rcp_f32_e32 v127, v127
	v_rcp_f32_e32 v128, v128
	v_rcp_f32_e32 v129, v129
	v_pk_mul_f32 v[74:75], v[74:75], v[122:123]
	v_pk_mul_f32 v[76:77], v[76:77], v[124:125]
	v_pk_mul_f32 v[78:79], v[78:79], v[126:127]
	v_pk_mul_f32 v[80:81], v[80:81], v[128:129]
	v_pk_mul_f32 v[74:75], v[82:83], v[74:75]
	v_pk_mul_f32 v[76:77], v[84:85], v[76:77]
	v_pk_mul_f32 v[78:79], v[86:87], v[78:79]
	v_pk_mul_f32 v[80:81], v[88:89], v[80:81]
	v_cvt_pk_bf16_f32 v138, v74, v75
	v_cvt_pk_bf16_f32 v139, v76, v77
	v_cvt_pk_bf16_f32 v140, v78, v79
	v_cvt_pk_bf16_f32 v141, v80, v81
	global_store_dwordx4 v[70:71], v[138:141], off
	v_lshl_add_u64 v[70:71], v[70:71], 0, s[10:11]
	s_branch .LBB0_707
